# epilogues: residual stores of EpiPanelNorm first pass delayed to pass end (3 instances); attention epilogue gain loads hoisted
# speedup vs baseline: 1.0333x; 1.0104x over previous
; __device__ __forceinline__ void attn_unit(LAS unsigned char* lds, const Args& A, int b, int h, int qrow0, int nkt) {
;     ...
;     __syncthreads();
;     if (map == 0) {
;         float ss = 0.f;
; #pragma unroll
;         for (int i = 0; i < 4; ++i)
; #pragma unroll
;             for (int r = 0; r < 16; ++r) { const float o = O[i][r] * inv - A.lam * ex[(i * 16 + r) * 64 + lane]; O[i][r] = o; ss += o * o; }
.LBB0_706:
	s_andn2_b64 vcc, exec, s[0:1]
	s_waitcnt lgkmcnt(0)
	s_barrier
	s_cbranch_vccnz .LBB0_671
	ds_read2st64_b32 v[66:67], v68 offset1:1
	v_mov_b32_e32 v166, v48
	v_readlane_b32 s0, v253, 16
	v_readlane_b32 s1, v253, 17
	s_lshl_b32 s42, s12, 8
	s_waitcnt lgkmcnt(0)
	v_mov_b32_e32 v65, v66
	v_pk_mul_f32 v[70:71], v[166:167], v[64:65]
	v_mov_b32_e32 v166, v49
	v_mov_b32_e32 v65, v67
	v_pk_mul_f32 v[66:67], v[166:167], v[64:65]
	v_mov_b32_e32 v166, v50
	v_sub_f32_e32 v49, v66, v67
	ds_read2st64_b32 v[66:67], v68 offset0:2 offset1:3
	v_sub_f32_e32 v48, v70, v71
	v_lshlrev_b32_e32 v160, 3, v184
	s_waitcnt lgkmcnt(0)
	v_mov_b32_e32 v65, v66
	v_pk_mul_f32 v[70:71], v[166:167], v[64:65]
	v_mov_b32_e32 v166, v51
	v_mov_b32_e32 v65, v67
	v_pk_mul_f32 v[66:67], v[166:167], v[64:65]
	v_mov_b32_e32 v166, v52
	v_sub_f32_e32 v51, v66, v67
	ds_read2st64_b32 v[66:67], v68 offset0:4 offset1:5
	v_sub_f32_e32 v50, v70, v71
	s_waitcnt lgkmcnt(0)
	v_mov_b32_e32 v65, v66
	v_pk_mul_f32 v[70:71], v[166:167], v[64:65]
	v_mov_b32_e32 v166, v53
	v_mov_b32_e32 v65, v67
	v_pk_mul_f32 v[66:67], v[166:167], v[64:65]
	v_mov_b32_e32 v166, v54
	v_sub_f32_e32 v53, v66, v67
	ds_read2st64_b32 v[66:67], v68 offset0:6 offset1:7
	v_sub_f32_e32 v52, v70, v71
	s_waitcnt lgkmcnt(0)
	v_mov_b32_e32 v65, v66
	v_pk_mul_f32 v[70:71], v[166:167], v[64:65]
	v_mov_b32_e32 v166, v55
	v_mov_b32_e32 v65, v67
	v_pk_mul_f32 v[66:67], v[166:167], v[64:65]
	v_mov_b32_e32 v166, v56
	v_sub_f32_e32 v55, v66, v67
	ds_read2st64_b32 v[66:67], v68 offset0:8 offset1:9
	v_sub_f32_e32 v54, v70, v71
	s_waitcnt lgkmcnt(0)
	v_mov_b32_e32 v65, v66
	v_pk_mul_f32 v[70:71], v[166:167], v[64:65]
	v_mov_b32_e32 v166, v57
	v_mov_b32_e32 v65, v67
	v_pk_mul_f32 v[66:67], v[166:167], v[64:65]
	v_mov_b32_e32 v166, v58
	v_sub_f32_e32 v57, v66, v67
	ds_read2st64_b32 v[66:67], v68 offset0:10 offset1:11
	v_sub_f32_e32 v56, v70, v71
	s_waitcnt lgkmcnt(0)
	v_mov_b32_e32 v65, v66
	v_pk_mul_f32 v[70:71], v[166:167], v[64:65]
	v_mov_b32_e32 v166, v59
	v_mov_b32_e32 v65, v67
	v_pk_mul_f32 v[66:67], v[166:167], v[64:65]
	v_mov_b32_e32 v166, v60
	v_sub_f32_e32 v59, v66, v67
	ds_read2st64_b32 v[66:67], v68 offset0:12 offset1:13
	v_sub_f32_e32 v58, v70, v71
	s_waitcnt lgkmcnt(0)
	v_mov_b32_e32 v65, v66
	v_pk_mul_f32 v[70:71], v[166:167], v[64:65]
	v_mov_b32_e32 v166, v61
	v_mov_b32_e32 v65, v67
	v_pk_mul_f32 v[66:67], v[166:167], v[64:65]
	v_mov_b32_e32 v166, v62
	v_sub_f32_e32 v61, v66, v67
	ds_read2st64_b32 v[66:67], v68 offset0:14 offset1:15
	v_sub_f32_e32 v60, v70, v71
	s_waitcnt lgkmcnt(0)
	v_mov_b32_e32 v65, v66
	v_pk_mul_f32 v[70:71], v[166:167], v[64:65]
	v_mov_b32_e32 v166, v63
	v_mov_b32_e32 v65, v67
	v_pk_mul_f32 v[66:67], v[166:167], v[64:65]
	v_mov_b32_e32 v166, v32
	v_sub_f32_e32 v63, v66, v67
	ds_read2st64_b32 v[66:67], v68 offset0:16 offset1:17
	v_sub_f32_e32 v62, v70, v71
	s_waitcnt lgkmcnt(0)
	v_mov_b32_e32 v65, v66
	v_pk_mul_f32 v[70:71], v[166:167], v[64:65]
	v_mov_b32_e32 v166, v33
	v_sub_f32_e32 v66, v70, v71
	ds_read2st64_b32 v[70:71], v68 offset0:18 offset1:19
	v_mov_b32_e32 v65, v67
	v_pk_mul_f32 v[32:33], v[166:167], v[64:65]
	v_mov_b32_e32 v166, v34
	v_sub_f32_e32 v32, v32, v33
	s_waitcnt lgkmcnt(0)
	v_mov_b32_e32 v65, v70
	v_pk_mul_f32 v[72:73], v[166:167], v[64:65]
	v_mov_b32_e32 v166, v35
	v_mov_b32_e32 v65, v71
	v_pk_mul_f32 v[70:71], v[166:167], v[64:65]
	v_mov_b32_e32 v166, v36
	v_sub_f32_e32 v33, v70, v71
	ds_read2st64_b32 v[70:71], v68 offset0:20 offset1:21
	v_sub_f32_e32 v34, v72, v73
	s_waitcnt lgkmcnt(0)
	v_mov_b32_e32 v65, v70
	v_pk_mul_f32 v[72:73], v[166:167], v[64:65]
	v_mov_b32_e32 v166, v37
	v_mov_b32_e32 v65, v71
	v_pk_mul_f32 v[70:71], v[166:167], v[64:65]
	v_mov_b32_e32 v166, v38
	v_sub_f32_e32 v35, v70, v71
	ds_read2st64_b32 v[70:71], v68 offset0:22 offset1:23
	v_sub_f32_e32 v36, v72, v73
	s_waitcnt lgkmcnt(0)
	v_mov_b32_e32 v65, v70
	v_pk_mul_f32 v[72:73], v[166:167], v[64:65]
	v_mov_b32_e32 v65, v71
	ds_read2st64_b32 v[70:71], v68 offset0:24 offset1:25
	v_mov_b32_e32 v166, v39
	v_pk_mul_f32 v[38:39], v[166:167], v[64:65]
	v_mov_b32_e32 v166, v40
	v_sub_f32_e32 v67, v72, v73
	s_waitcnt lgkmcnt(0)
	v_mov_b32_e32 v65, v70
	v_pk_mul_f32 v[72:73], v[166:167], v[64:65]
	v_mov_b32_e32 v65, v71
	ds_read2st64_b32 v[70:71], v68 offset0:26 offset1:27
	v_mov_b32_e32 v166, v41
	v_pk_mul_f32 v[40:41], v[166:167], v[64:65]
	v_mov_b32_e32 v166, v42
	v_sub_f32_e32 v37, v40, v41
	s_waitcnt lgkmcnt(0)
	v_mov_b32_e32 v65, v70
	v_pk_mul_f32 v[40:41], v[166:167], v[64:65]
	v_mov_b32_e32 v65, v71
	ds_read2st64_b32 v[70:71], v68 offset0:28 offset1:29
	v_mov_b32_e32 v166, v43
	v_pk_mul_f32 v[42:43], v[166:167], v[64:65]
	v_mov_b32_e32 v166, v44
	v_sub_f32_e32 v41, v40, v41
	s_waitcnt lgkmcnt(0)
	v_mov_b32_e32 v65, v70
	v_sub_f32_e32 v40, v42, v43
	v_pk_mul_f32 v[42:43], v[166:167], v[64:65]
	v_mov_b32_e32 v65, v71
	ds_read2st64_b32 v[70:71], v68 offset0:30 offset1:31
	v_mov_b32_e32 v166, v45
	v_pk_mul_f32 v[44:45], v[166:167], v[64:65]
	v_mov_b32_e32 v166, v46
	v_sub_f32_e32 v43, v42, v43
	s_waitcnt lgkmcnt(0)
	v_mov_b32_e32 v65, v70
	v_sub_f32_e32 v42, v44, v45
	v_pk_mul_f32 v[44:45], v[166:167], v[64:65]
	v_mov_b32_e32 v166, v47
	v_mov_b32_e32 v65, v71
	v_pk_mul_f32 v[46:47], v[166:167], v[64:65]
	v_sub_f32_e32 v45, v44, v45
	v_sub_f32_e32 v44, v46, v47
	ds_read2st64_b32 v[46:47], v68 offset0:32 offset1:33
	v_mov_b32_e32 v166, v16
	v_sub_f32_e32 v39, v38, v39
	v_sub_f32_e32 v38, v72, v73
	s_waitcnt lgkmcnt(0)
	v_mov_b32_e32 v65, v46
	v_pk_mul_f32 v[70:71], v[166:167], v[64:65]
	v_mov_b32_e32 v166, v17
	v_sub_f32_e32 v46, v70, v71
	ds_read2st64_b32 v[70:71], v68 offset0:34 offset1:35
	v_mov_b32_e32 v65, v47
	v_pk_mul_f32 v[16:17], v[166:167], v[64:65]
	v_mov_b32_e32 v166, v18
	v_sub_f32_e32 v16, v16, v17
	s_waitcnt lgkmcnt(0)
; __device__ __forceinline__ void attn_unit(LAS unsigned char* lds, const Args& A, int b, int h, int qrow0, int nkt) {
;     ...
;             for (int r = 0; r < 16; ++r) { const float o = O[i][r] * inv - A.lam * ex[(i * 16 + r) * 64 + lane]; O[i][r] = o; ss += o * o; }
;         ss += __shfl_xor(ss, 32);
	v_mov_b32_e32 v65, v70
	v_pk_mul_f32 v[72:73], v[166:167], v[64:65]
	v_mov_b32_e32 v166, v19
	v_mov_b32_e32 v65, v71
	v_pk_mul_f32 v[70:71], v[166:167], v[64:65]
	v_mov_b32_e32 v166, v20
	v_sub_f32_e32 v17, v70, v71
	ds_read2st64_b32 v[70:71], v68 offset0:36 offset1:37
	v_sub_f32_e32 v18, v72, v73
	s_waitcnt lgkmcnt(0)
	v_mov_b32_e32 v65, v70
	v_pk_mul_f32 v[72:73], v[166:167], v[64:65]
	v_mov_b32_e32 v166, v21
	v_mov_b32_e32 v65, v71
	v_pk_mul_f32 v[70:71], v[166:167], v[64:65]
	v_mov_b32_e32 v166, v22
	v_sub_f32_e32 v19, v70, v71
	ds_read2st64_b32 v[70:71], v68 offset0:38 offset1:39
	v_sub_f32_e32 v20, v72, v73
	s_waitcnt lgkmcnt(0)
	v_mov_b32_e32 v65, v70
	v_pk_mul_f32 v[72:73], v[166:167], v[64:65]
	v_mov_b32_e32 v65, v71
	ds_read2st64_b32 v[70:71], v68 offset0:40 offset1:41
	v_mov_b32_e32 v166, v23
	v_pk_mul_f32 v[22:23], v[166:167], v[64:65]
	v_mov_b32_e32 v166, v24
	v_sub_f32_e32 v47, v72, v73
	s_waitcnt lgkmcnt(0)
	v_mov_b32_e32 v65, v70
	v_pk_mul_f32 v[72:73], v[166:167], v[64:65]
	v_mov_b32_e32 v65, v71
	ds_read2st64_b32 v[70:71], v68 offset0:42 offset1:43
	v_mov_b32_e32 v166, v25
	v_pk_mul_f32 v[24:25], v[166:167], v[64:65]
	v_mov_b32_e32 v166, v26
	v_sub_f32_e32 v21, v24, v25
	s_waitcnt lgkmcnt(0)
	v_mov_b32_e32 v65, v70
	v_pk_mul_f32 v[24:25], v[166:167], v[64:65]
	v_mov_b32_e32 v65, v71
	ds_read2st64_b32 v[70:71], v68 offset0:44 offset1:45
	v_mov_b32_e32 v166, v27
	v_pk_mul_f32 v[26:27], v[166:167], v[64:65]
	v_mov_b32_e32 v166, v28
	v_sub_f32_e32 v25, v24, v25
	s_waitcnt lgkmcnt(0)
	v_mov_b32_e32 v65, v70
	v_sub_f32_e32 v24, v26, v27
	v_pk_mul_f32 v[26:27], v[166:167], v[64:65]
	v_mov_b32_e32 v166, v29
	v_mov_b32_e32 v65, v71
	v_pk_mul_f32 v[28:29], v[166:167], v[64:65]
	v_sub_f32_e32 v27, v26, v27
	v_sub_f32_e32 v26, v28, v29
	ds_read2st64_b32 v[28:29], v68 offset0:46 offset1:47
	v_mov_b32_e32 v166, v30
	v_sub_f32_e32 v23, v22, v23
	v_sub_f32_e32 v22, v72, v73
	s_waitcnt lgkmcnt(0)
	v_mov_b32_e32 v65, v28
	v_pk_mul_f32 v[70:71], v[166:167], v[64:65]
	v_mov_b32_e32 v166, v31
	ds_read2st64_b32 v[30:31], v68 offset0:48 offset1:49
	v_mov_b32_e32 v65, v29
	v_pk_mul_f32 v[28:29], v[166:167], v[64:65]
	v_mov_b32_e32 v166, v0
	v_sub_f32_e32 v69, v70, v71
	s_waitcnt lgkmcnt(0)
	v_mov_b32_e32 v65, v30
	v_pk_mul_f32 v[70:71], v[166:167], v[64:65]
	v_mov_b32_e32 v166, v1
	v_mov_b32_e32 v65, v31
	v_pk_mul_f32 v[0:1], v[166:167], v[64:65]
	v_sub_f32_e32 v29, v28, v29
	v_sub_f32_e32 v28, v0, v1
	ds_read2st64_b32 v[0:1], v68 offset0:50 offset1:51
	v_mov_b32_e32 v166, v2
	v_sub_f32_e32 v30, v70, v71
	s_waitcnt lgkmcnt(0)
	v_mov_b32_e32 v65, v0
	v_pk_mul_f32 v[70:71], v[166:167], v[64:65]
	v_mov_b32_e32 v166, v3
	v_mov_b32_e32 v65, v1
	v_pk_mul_f32 v[0:1], v[166:167], v[64:65]
	v_mov_b32_e32 v166, v4
	v_sub_f32_e32 v31, v0, v1
	ds_read2st64_b32 v[0:1], v68 offset0:52 offset1:53
	v_sub_f32_e32 v70, v70, v71
	s_waitcnt lgkmcnt(0)
	v_mov_b32_e32 v65, v0
	v_pk_mul_f32 v[2:3], v[166:167], v[64:65]
	v_mov_b32_e32 v166, v5
	v_mov_b32_e32 v65, v1
	v_pk_mul_f32 v[0:1], v[166:167], v[64:65]
	v_mov_b32_e32 v166, v6
	v_sub_f32_e32 v71, v0, v1
	ds_read2st64_b32 v[0:1], v68 offset0:54 offset1:55
	v_sub_f32_e32 v72, v2, v3
	s_waitcnt lgkmcnt(0)
	v_mov_b32_e32 v65, v0
	v_pk_mul_f32 v[2:3], v[166:167], v[64:65]
	v_mov_b32_e32 v166, v7
	v_mov_b32_e32 v65, v1
	v_pk_mul_f32 v[0:1], v[166:167], v[64:65]
	v_mov_b32_e32 v166, v8
	v_mul_f32_e32 v8, v48, v48
	v_fmac_f32_e32 v8, v49, v49
	v_fmac_f32_e32 v8, v50, v50
	v_fmac_f32_e32 v8, v51, v51
	v_fmac_f32_e32 v8, v52, v52
	v_fmac_f32_e32 v8, v53, v53
	v_fmac_f32_e32 v8, v54, v54
	v_fmac_f32_e32 v8, v55, v55
	v_fmac_f32_e32 v8, v56, v56
	v_fmac_f32_e32 v8, v57, v57
	v_fmac_f32_e32 v8, v58, v58
	v_fmac_f32_e32 v8, v59, v59
	v_fmac_f32_e32 v8, v60, v60
	v_fmac_f32_e32 v8, v61, v61
	v_fmac_f32_e32 v8, v62, v62
	v_fmac_f32_e32 v8, v63, v63
	v_fmac_f32_e32 v8, v66, v66
	v_fmac_f32_e32 v8, v32, v32
	v_fmac_f32_e32 v8, v34, v34
	v_fmac_f32_e32 v8, v33, v33
	v_fmac_f32_e32 v8, v36, v36
	v_fmac_f32_e32 v8, v35, v35
	v_fmac_f32_e32 v8, v67, v67
	v_fmac_f32_e32 v8, v39, v39
	v_fmac_f32_e32 v8, v38, v38
	v_fmac_f32_e32 v8, v37, v37
	v_fmac_f32_e32 v8, v41, v41
	v_fmac_f32_e32 v8, v40, v40
	v_fmac_f32_e32 v8, v43, v43
	v_fmac_f32_e32 v8, v42, v42
	v_fmac_f32_e32 v8, v45, v45
	v_fmac_f32_e32 v8, v44, v44
	v_fmac_f32_e32 v8, v46, v46
	v_fmac_f32_e32 v8, v16, v16
	v_fmac_f32_e32 v8, v18, v18
	v_fmac_f32_e32 v8, v17, v17
	v_sub_f32_e32 v75, v0, v1
	ds_read2st64_b32 v[0:1], v68 offset0:56 offset1:57
	v_fmac_f32_e32 v8, v20, v20
	v_fmac_f32_e32 v8, v19, v19
	v_fmac_f32_e32 v8, v47, v47
	v_fmac_f32_e32 v8, v23, v23
	v_fmac_f32_e32 v8, v22, v22
	s_waitcnt lgkmcnt(0)
	v_mov_b32_e32 v65, v0
	v_fmac_f32_e32 v8, v21, v21
	v_sub_f32_e32 v76, v2, v3
	v_pk_mul_f32 v[2:3], v[166:167], v[64:65]
	v_mov_b32_e32 v166, v9
	v_mov_b32_e32 v65, v1
	v_fmac_f32_e32 v8, v25, v25
	v_pk_mul_f32 v[0:1], v[166:167], v[64:65]
	v_fmac_f32_e32 v8, v24, v24
	v_sub_f32_e32 v73, v0, v1
	ds_read2st64_b32 v[0:1], v68 offset0:58 offset1:59
	v_fmac_f32_e32 v8, v27, v27
	v_fmac_f32_e32 v8, v26, v26
	v_fmac_f32_e32 v8, v69, v69
	v_fmac_f32_e32 v8, v29, v29
	v_fmac_f32_e32 v8, v30, v30
	v_mov_b32_e32 v166, v10
	s_waitcnt lgkmcnt(0)
	v_mov_b32_e32 v65, v0
	v_fmac_f32_e32 v8, v28, v28
	v_sub_f32_e32 v74, v2, v3
	v_pk_mul_f32 v[2:3], v[166:167], v[64:65]
	v_mov_b32_e32 v166, v11
	v_mov_b32_e32 v65, v1
	v_fmac_f32_e32 v8, v70, v70
	v_pk_mul_f32 v[0:1], v[166:167], v[64:65]
	v_fmac_f32_e32 v8, v31, v31
	v_sub_f32_e32 v10, v0, v1
	ds_read2st64_b32 v[0:1], v68 offset0:60 offset1:61
	v_fmac_f32_e32 v8, v72, v72
	v_fmac_f32_e32 v8, v71, v71
	v_sub_f32_e32 v77, v2, v3
	ds_read2st64_b32 v[2:3], v68 offset0:62 offset1:63
	v_fmac_f32_e32 v8, v76, v76
	v_fmac_f32_e32 v8, v75, v75
	v_fmac_f32_e32 v8, v74, v74
	s_waitcnt lgkmcnt(1)
; __device__ __forceinline__ void attn_unit(LAS unsigned char* lds, const Args& A, int b, int h, int qrow0, int nkt) {
;     ...
;             for (int r = 0; r < 16; ++r) { const float o = O[i][r] * inv - A.lam * ex[(i * 16 + r) * 64 + lane]; O[i][r] = o; ss += o * o; }
;         ss += __shfl_xor(ss, 32);
;         const float rstd = __builtin_amdgcn_rsqf(ss * (1.f / 128.f) + EPSV) * A.omli;
;         bf16_t* dst = A.MIXA + (size_t)(qrow0 + qg * 32 + r32) * DM + h * 128 + 4 * hi;
; #pragma unroll
;         for (int i = 0; i < 4; ++i)
; #pragma unroll
;             for (int rq = 0; rq < 4; ++rq) {
;                 const int d0 = 32 * i + 8 * rq;
;                 const f32x4 gg = *(const f32x4*)(A.subln + d0 + 4 * hi);
	v_pk_mul_f32 v[0:1], v[168:169], v[0:1]
	v_fmac_f32_e32 v8, v73, v73
	v_pk_fma_f32 v[4:5], v[12:13], v[64:65], v[0:1] op_sel_hi:[1,0,1] neg_lo:[0,0,1] neg_hi:[0,0,1]
	v_fmac_f32_e32 v8, v77, v77
	v_pk_mul_f32 v[0:1], v[4:5], v[4:5]
	s_waitcnt lgkmcnt(0)
	v_pk_mul_f32 v[2:3], v[168:169], v[2:3]
	v_fmac_f32_e32 v8, v10, v10
	v_pk_fma_f32 v[6:7], v[14:15], v[64:65], v[2:3] op_sel_hi:[1,0,1] neg_lo:[0,0,1] neg_hi:[0,0,1]
	v_add_f32_e32 v0, v8, v0
	v_pk_mul_f32 v[2:3], v[6:7], v[6:7]
	v_add_f32_e32 v0, v0, v1
	v_add_f32_e32 v0, v0, v2
	v_add_f32_e32 v0, v0, v3
	ds_bpermute_b32 v1, v214, v0
	s_waitcnt lgkmcnt(0)
	v_add_f32_e32 v0, v0, v1
	v_fmamk_f32 v0, v0, 0x3c000000, v193
	v_rsq_f32_e32 v0, v0
	s_nop 0
	v_mul_f32_e32 v11, v215, v0
	v_lshlrev_b64 v[0:1], 11, v[172:173]
	v_lshl_add_u64 v[0:1], s[0:1], 0, v[0:1]
	v_lshl_add_u64 v[0:1], v[0:1], 0, s[42:43]
	v_lshl_add_u64 v[8:9], v[0:1], 0, v[160:161]
	global_load_dwordx4 v[80:83], v170, s[4:5]
	global_load_dwordx4 v[84:87], v170, s[4:5] offset:32
	global_load_dwordx4 v[88:91], v170, s[4:5] offset:64
	global_load_dwordx4 v[92:95], v170, s[4:5] offset:96
	global_load_dwordx4 v[96:99], v170, s[4:5] offset:128
	global_load_dwordx4 v[100:103], v170, s[4:5] offset:160
	global_load_dwordx4 v[104:107], v170, s[4:5] offset:192
	global_load_dwordx4 v[108:111], v170, s[4:5] offset:224
	global_load_dwordx4 v[112:115], v170, s[4:5] offset:256
	global_load_dwordx4 v[116:119], v170, s[4:5] offset:288
	global_load_dwordx4 v[120:123], v170, s[4:5] offset:320
	global_load_dwordx4 v[124:127], v170, s[4:5] offset:352
	global_load_dwordx4 v[128:131], v170, s[4:5] offset:384
	global_load_dwordx4 v[132:135], v170, s[4:5] offset:416
	global_load_dwordx4 v[136:139], v170, s[4:5] offset:448
	global_load_dwordx4 v[140:143], v170, s[4:5] offset:480
	s_waitcnt vmcnt(0)
; __device__ __forceinline__ u32x2 pack4(f32x4 v) { u32x2 w; w.x = cvt_pk_bf16(v[0], v[1]); w.y = cvt_pk_bf16(v[2], v[3]); return w; }
; __device__ __forceinline__ void attn_unit(LAS unsigned char* lds, const Args& A, int b, int h, int qrow0, int nkt) {
;     ...
;         bf16_t* dst = A.MIXA + (size_t)(qrow0 + qg * 32 + r32) * DM + h * 128 + 4 * hi;
; #pragma unroll
;         for (int i = 0; i < 4; ++i)
; #pragma unroll
;             for (int rq = 0; rq < 4; ++rq) {
;                 const int d0 = 32 * i + 8 * rq;
;                 const f32x4 gg = *(const f32x4*)(A.subln + d0 + 4 * hi);
;                 f32x4 v = {O[i][4 * rq] * rstd * gg[0], O[i][4 * rq + 1] * rstd * gg[1], O[i][4 * rq + 2] * rstd * gg[2], O[i][4 * rq + 3] * rstd * gg[3]};
;                 *(u32x2*)(dst + d0) = pack4(v);
;             }
	v_mul_f32_e32 v12, v48, v11
	v_mul_f32_e32 v10, v10, v11
	v_mul_f32_e32 v4, v4, v11
	v_mul_f32_e32 v0, v80, v12
	v_mul_f32_e32 v12, v49, v11
	v_mul_f32_e32 v1, v81, v12
	v_mul_f32_e32 v12, v50, v11
	v_mul_f32_e32 v2, v82, v12
	v_mul_f32_e32 v12, v51, v11
	v_mul_f32_e32 v3, v83, v12
	v_cvt_pk_bf16_f32 v0, v0, v1
	v_cvt_pk_bf16_f32 v1, v2, v3
	global_store_dwordx2 v[8:9], v[0:1], off
	v_mul_f32_e32 v12, v52, v11
	v_mul_f32_e32 v144, v84, v12
	v_mul_f32_e32 v12, v53, v11
	v_mul_f32_e32 v145, v85, v12
	v_mul_f32_e32 v12, v54, v11
	v_mul_f32_e32 v146, v86, v12
	v_mul_f32_e32 v12, v55, v11
	v_mul_f32_e32 v147, v87, v12
	v_cvt_pk_bf16_f32 v144, v144, v145
	v_cvt_pk_bf16_f32 v145, v146, v147
	global_store_dwordx2 v[8:9], v[144:145], off offset:16
	v_mul_f32_e32 v12, v56, v11
	v_mul_f32_e32 v0, v88, v12
	v_mul_f32_e32 v12, v57, v11
	v_mul_f32_e32 v1, v89, v12
	v_mul_f32_e32 v12, v58, v11
	v_mul_f32_e32 v2, v90, v12
	v_mul_f32_e32 v12, v59, v11
	v_mul_f32_e32 v3, v91, v12
	v_cvt_pk_bf16_f32 v0, v0, v1
	v_cvt_pk_bf16_f32 v1, v2, v3
	global_store_dwordx2 v[8:9], v[0:1], off offset:32
	v_mul_f32_e32 v12, v60, v11
	v_mul_f32_e32 v144, v92, v12
	v_mul_f32_e32 v12, v61, v11
	v_mul_f32_e32 v145, v93, v12
	v_mul_f32_e32 v12, v62, v11
	v_mul_f32_e32 v146, v94, v12
	v_mul_f32_e32 v12, v63, v11
	v_mul_f32_e32 v147, v95, v12
	v_cvt_pk_bf16_f32 v144, v144, v145
	v_cvt_pk_bf16_f32 v145, v146, v147
	global_store_dwordx2 v[8:9], v[144:145], off offset:48
	v_mul_f32_e32 v12, v66, v11
	v_mul_f32_e32 v0, v96, v12
	v_mul_f32_e32 v12, v32, v11
	v_mul_f32_e32 v1, v97, v12
	v_mul_f32_e32 v12, v34, v11
	v_mul_f32_e32 v2, v98, v12
	v_mul_f32_e32 v12, v33, v11
	v_mul_f32_e32 v3, v99, v12
	v_cvt_pk_bf16_f32 v0, v0, v1
	v_cvt_pk_bf16_f32 v1, v2, v3
	global_store_dwordx2 v[8:9], v[0:1], off offset:64
	v_mul_f32_e32 v12, v36, v11
	v_mul_f32_e32 v144, v100, v12
	v_mul_f32_e32 v12, v35, v11
	v_mul_f32_e32 v145, v101, v12
	v_mul_f32_e32 v12, v67, v11
	v_mul_f32_e32 v146, v102, v12
	v_mul_f32_e32 v12, v39, v11
	v_mul_f32_e32 v147, v103, v12
	v_cvt_pk_bf16_f32 v144, v144, v145
	v_cvt_pk_bf16_f32 v145, v146, v147
	global_store_dwordx2 v[8:9], v[144:145], off offset:80
	v_mul_f32_e32 v12, v38, v11
	v_mul_f32_e32 v0, v104, v12
	v_mul_f32_e32 v12, v37, v11
	v_mul_f32_e32 v1, v105, v12
	v_mul_f32_e32 v12, v41, v11
	v_mul_f32_e32 v2, v106, v12
	v_mul_f32_e32 v12, v40, v11
	v_mul_f32_e32 v3, v107, v12
	v_cvt_pk_bf16_f32 v0, v0, v1
	v_cvt_pk_bf16_f32 v1, v2, v3
	global_store_dwordx2 v[8:9], v[0:1], off offset:96
	v_mul_f32_e32 v12, v43, v11
	v_mul_f32_e32 v144, v108, v12
	v_mul_f32_e32 v12, v42, v11
	v_mul_f32_e32 v145, v109, v12
	v_mul_f32_e32 v12, v45, v11
	v_mul_f32_e32 v146, v110, v12
	v_mul_f32_e32 v12, v44, v11
	v_mul_f32_e32 v147, v111, v12
	v_cvt_pk_bf16_f32 v144, v144, v145
	v_cvt_pk_bf16_f32 v145, v146, v147
	global_store_dwordx2 v[8:9], v[144:145], off offset:112
	v_mul_f32_e32 v12, v46, v11
	v_mul_f32_e32 v0, v112, v12
	v_mul_f32_e32 v12, v16, v11
	v_mul_f32_e32 v1, v113, v12
	v_mul_f32_e32 v12, v18, v11
	v_mul_f32_e32 v2, v114, v12
	v_mul_f32_e32 v12, v17, v11
	v_mul_f32_e32 v3, v115, v12
	v_cvt_pk_bf16_f32 v0, v0, v1
	v_cvt_pk_bf16_f32 v1, v2, v3
	global_store_dwordx2 v[8:9], v[0:1], off offset:128
	v_mul_f32_e32 v12, v20, v11
	v_mul_f32_e32 v144, v116, v12
	v_mul_f32_e32 v12, v19, v11
	v_mul_f32_e32 v145, v117, v12
	v_mul_f32_e32 v12, v47, v11
	v_mul_f32_e32 v146, v118, v12
	v_mul_f32_e32 v12, v23, v11
	v_mul_f32_e32 v147, v119, v12
	v_cvt_pk_bf16_f32 v144, v144, v145
	v_cvt_pk_bf16_f32 v145, v146, v147
	global_store_dwordx2 v[8:9], v[144:145], off offset:144
	v_mul_f32_e32 v12, v22, v11
	v_mul_f32_e32 v0, v120, v12
	v_mul_f32_e32 v12, v21, v11
	v_mul_f32_e32 v1, v121, v12
	v_mul_f32_e32 v12, v25, v11
	v_mul_f32_e32 v2, v122, v12
	v_mul_f32_e32 v12, v24, v11
	v_mul_f32_e32 v3, v123, v12
	v_cvt_pk_bf16_f32 v0, v0, v1
	v_cvt_pk_bf16_f32 v1, v2, v3
	global_store_dwordx2 v[8:9], v[0:1], off offset:160
	v_mul_f32_e32 v12, v27, v11
	v_mul_f32_e32 v144, v124, v12
	v_mul_f32_e32 v12, v26, v11
	v_mul_f32_e32 v145, v125, v12
	v_mul_f32_e32 v12, v69, v11
	v_mul_f32_e32 v146, v126, v12
	v_mul_f32_e32 v12, v29, v11
	v_mul_f32_e32 v147, v127, v12
	v_cvt_pk_bf16_f32 v144, v144, v145
	v_cvt_pk_bf16_f32 v145, v146, v147
	global_store_dwordx2 v[8:9], v[144:145], off offset:176
	v_mul_f32_e32 v12, v30, v11
	v_mul_f32_e32 v0, v128, v12
	v_mul_f32_e32 v12, v28, v11
	v_mul_f32_e32 v1, v129, v12
	v_mul_f32_e32 v12, v70, v11
	v_mul_f32_e32 v2, v130, v12
	v_mul_f32_e32 v12, v31, v11
	v_mul_f32_e32 v3, v131, v12
	v_cvt_pk_bf16_f32 v0, v0, v1
	v_cvt_pk_bf16_f32 v1, v2, v3
	global_store_dwordx2 v[8:9], v[0:1], off offset:192
	v_mul_f32_e32 v12, v72, v11
	v_mul_f32_e32 v144, v132, v12
	v_mul_f32_e32 v12, v71, v11
	v_mul_f32_e32 v145, v133, v12
	v_mul_f32_e32 v12, v76, v11
	v_mul_f32_e32 v146, v134, v12
	v_mul_f32_e32 v12, v75, v11
	v_mul_f32_e32 v147, v135, v12
	v_cvt_pk_bf16_f32 v144, v144, v145
	v_cvt_pk_bf16_f32 v145, v146, v147
	global_store_dwordx2 v[8:9], v[144:145], off offset:208
	v_mul_f32_e32 v12, v74, v11
	v_mul_f32_e32 v0, v136, v12
	v_mul_f32_e32 v12, v73, v11
	v_mul_f32_e32 v1, v137, v12
	v_mul_f32_e32 v12, v77, v11
	v_mul_f32_e32 v2, v138, v12
	v_mul_f32_e32 v3, v139, v10
	v_cvt_pk_bf16_f32 v0, v0, v1
	v_cvt_pk_bf16_f32 v1, v2, v3
	global_store_dwordx2 v[8:9], v[0:1], off offset:224
	v_mul_f32_e32 v144, v140, v4
	v_mul_f32_e32 v4, v5, v11
	v_mul_f32_e32 v145, v141, v4
	v_mul_f32_e32 v4, v6, v11
	v_mul_f32_e32 v146, v142, v4
	v_mul_f32_e32 v4, v7, v11
	v_mul_f32_e32 v147, v143, v4
	v_cvt_pk_bf16_f32 v144, v144, v145
	v_cvt_pk_bf16_f32 v145, v146, v147
	global_store_dwordx2 v[8:9], v[144:145], off offset:240
	s_branch .LBB0_671

; #define LAS __attribute__((address_space(3)))
; #define PG8_WAIT_V(n) asm volatile("s_waitcnt vmcnt(" #n ")" ::: "memory")
; #define PG8_BAR __builtin_amdgcn_s_barrier()
; #define EF_LOAD(buf, g_) do { const float* xp_ = xi + (size_t)(((g_) >> 2) * 128 + ((g_) & 3) * 16) * DM; \
;             _Pragma("unroll") for (int bj = 0; bj < 2; ++bj) _Pragma("unroll") for (int n = 0; n < 2; ++n) xv[buf][bj][n] = *(const f32x4*)(xp_ + bj * 128 + n * 4); } while (0)
; template <class Epi, class Sched, bool ALIGN_EPI>
; __device__ __forceinline__ void gemm_phase(LAS unsigned char* lds, const Gemm g, const Sched& S, const Epi& E) {
;     ...
;     PG8_WAIT_V(0);
;     if constexpr (!ALIGN_EPI) { if (wr == 0) PG8_BAR; }
;     PG8_BAR;
;     if constexpr (Epi::AFTER_DRAIN) E.fused(acc, cur, wr, wc, fr, fq, lds, wid, lane);
;     __device__ __forceinline__ void fused(Acc& acc, const pg8::Unit& u, int wr, int wc, int fr, int fq, LAS unsigned char* lds, int wid, int lane) const {
;         const int tile0 = u.pm * 256, colb = u.pn * 256 + wc * 32 + 8 * fq, rloc = wr * 64 + fr;
;         const float* xi = xin + (size_t)(tile0 + rloc) * DM + colb;
;         float* xo = out + (size_t)(tile0 + rloc) * DM + colb;
;         const float* gp = mod + (tile0 >> 11) * 6144 + goff + colb;
;         f32x4 gt[2][2];
; #pragma unroll
;         for (int bj = 0; bj < 2; ++bj)
; #pragma unroll
;             for (int n = 0; n < 2; ++n) gt[bj][n] = *(const f32x4*)(gp + bj * 128 + n * 4);
;         f32x4 xv[1][2][2];
;     ...
;         LAS float* P = (LAS float*)lds;
;         LAS float* S = (LAS float*)(lds + 4096);
; #pragma unroll
;         for (int g_ = 0; g_ < 8; ++g_) {
;             EF_LOAD(0, g_);
;             float sq = 0.f;
; #pragma unroll
;             for (int bj = 0; bj < 2; ++bj)
; #pragma unroll
;                 for (int n = 0; n < 2; ++n) { const f32x4 xn = xv[0][bj][n] + gt[bj][n] * acc[g_ >> 2][bj][g_ & 3][n]; acc[g_ >> 2][bj][g_ & 3][n] = xn;
;                     if (MODE == 1) *(f32x4*)(xo + (size_t)((g_ >> 2) * 128 + (g_ & 3) * 16) * DM + bj * 128 + n * 4) = xn;
;                     sq += (xn[0] * xn[0] + xn[1] * xn[1]) + (xn[2] * xn[2] + xn[3] * xn[3]); }
;             sq += __shfl_xor(sq, 16); sq += __shfl_xor(sq, 32);
;             if (fq == 0) P[((g_ >> 2) * 128 + wr * 64 + (g_ & 3) * 16 + fr) * 4 + wc] = sq;
.LBB0_947:
	s_lshl_b32 s0, s9, 5
	s_lshl_b32 s1, s8, 8
	v_lshrrev_b32_e32 v128, 1, v170
	s_or_b32 s0, s1, s0
	v_and_or_b32 v154, v128, 24, s0
	s_lshr_b32 s0, s6, 3
	s_mulk_i32 s0, 0x1800
	s_ashr_i32 s1, s0, 31
	s_lshl_b32 s10, s6, 8
	s_lshl_b64 s[0:1], s[0:1], 2
	v_ashrrev_i32_e32 v155, 31, v154
	s_add_u32 s0, s48, s0
	s_addc_u32 s1, s49, s1
	v_lshlrev_b64 v[156:157], 2, v[154:155]
	v_add_u32_e32 v158, s10, v144
	v_lshl_add_u64 v[152:153], s[0:1], 0, v[156:157]
	v_ashrrev_i32_e32 v159, 31, v158
	v_add_co_u32_e32 v128, vcc, s21, v152
	v_readlane_b32 s0, v255, 28
	v_lshlrev_b64 v[150:151], 12, v[158:159]
	v_addc_co_u32_e32 v129, vcc, 0, v153, vcc
	v_readlane_b32 s1, v255, 29
	s_waitcnt vmcnt(0)
	s_barrier
	global_load_dwordx4 v[140:143], v[128:129], off
	v_lshl_add_u64 v[128:129], s[0:1], 0, v[150:151]
	v_lshl_add_u64 v[168:169], v[128:129], 0, v[156:157]
	global_load_dwordx4 v[146:149], v[168:169], off offset:16
	global_load_dwordx4 v[162:165], v[168:169], off
	s_mov_b64 s[0:1], 0x2000
	v_lshl_add_u64 v[128:129], v[152:153], 0, s[0:1]
	global_load_dwordx4 v[136:139], v[128:129], off offset:16
	global_load_dwordx4 v[132:135], v[128:129], off offset:512
	global_load_dwordx4 v[172:175], v[168:169], off offset:512
	global_load_dwordx4 v[176:179], v[168:169], off offset:528
	s_nop 0
	global_load_dwordx4 v[128:131], v[128:129], off offset:528
	v_readlane_b32 s52, v252, 0
	v_readlane_b32 s54, v252, 2
	v_readlane_b32 s55, v252, 3
	s_lshl_b32 s4, s9, 2
	v_and_b32_e32 v160, 63, v170
	v_lshl_add_u64 v[150:151], s[54:55], 0, v[150:151]
	v_lshl_add_u64 v[166:167], v[150:151], 0, v[156:157]
	s_add_i32 s9, s4, 0
	v_cmp_gt_u32_e64 s[0:1], 16, v160
	v_lshl_add_u32 v144, v144, 4, s9
	v_readlane_b32 s53, v252, 1
	v_readlane_b32 s56, v252, 4
	v_readlane_b32 s57, v252, 5
	v_readlane_b32 s58, v252, 6
	v_readlane_b32 s59, v252, 7
	s_waitcnt vmcnt(0)
	v_pk_fma_f32 v[102:103], v[102:103], v[138:139], v[148:149]
	v_pk_fma_f32 v[98:99], v[98:99], v[142:143], v[164:165]
	v_pk_fma_f32 v[96:97], v[96:97], v[140:141], v[162:163]
	v_pk_fma_f32 v[100:101], v[100:101], v[136:137], v[146:147]
	v_pk_fma_f32 v[50:51], v[50:51], v[134:135], v[174:175]
	v_pk_fma_f32 v[48:49], v[48:49], v[132:133], v[172:173]
	v_mul_f32_e32 v145, v97, v97
	v_mul_f32_e32 v146, v99, v99
	v_mul_f32_e32 v147, v101, v101
	v_mul_f32_e32 v148, v103, v103
	v_pk_fma_f32 v[54:55], v[54:55], v[130:131], v[178:179]
	v_pk_fma_f32 v[52:53], v[52:53], v[128:129], v[176:177]
	v_mul_f32_e32 v149, v49, v49
	v_mul_f32_e32 v150, v51, v51
	v_fmac_f32_e32 v145, v96, v96
	v_fmac_f32_e32 v146, v98, v98
	v_fmac_f32_e32 v147, v100, v100
	v_fmac_f32_e32 v148, v102, v102
	v_mul_f32_e32 v151, v53, v53
	v_mul_f32_e32 v162, v55, v55
	v_fmac_f32_e32 v149, v48, v48
	v_fmac_f32_e32 v150, v50, v50
	v_add_f32_e32 v145, v145, v146
	v_add_f32_e32 v146, v147, v148
	v_fmac_f32_e32 v151, v52, v52
	v_fmac_f32_e32 v162, v54, v54
	v_add_f32_e32 v147, v149, v150
	v_add_f32_e32 v145, v145, v146
	v_add_f32_e32 v145, v145, v147
	v_add_f32_e32 v146, v151, v162
	v_add_f32_e32 v145, v145, v146
	ds_bpermute_b32 v146, v213, v145
	s_waitcnt lgkmcnt(0)
	v_add_f32_e32 v145, v145, v146
	ds_bpermute_b32 v146, v214, v145
	s_and_saveexec_b64 s[4:5], s[0:1]
	s_cbranch_execz .LBB0_949
	s_waitcnt lgkmcnt(0)
	v_add_f32_e32 v145, v145, v146
	ds_write_b32 v144, v145
.LBB0_949:
	s_or_b64 exec, exec, s[4:5]
	v_add_co_u32_e32 v150, vcc, 0x10000, v168
	v_lshl_add_u64 v[162:163], v[168:169], 0, s[88:89]
	s_nop 0
	v_addc_co_u32_e32 v151, vcc, 0, v169, vcc
	s_waitcnt lgkmcnt(0)
	global_load_dwordx4 v[146:149], v[150:151], off
	s_mov_b64 s[4:5], 0x10200
	global_load_dwordx4 v[162:165], v[162:163], off offset:16
	s_nop 0
	global_load_dwordx4 v[172:175], v[150:151], off offset:512
	v_lshl_add_u64 v[150:151], v[168:169], 0, s[4:5]
	global_load_dwordx4 v[176:179], v[150:151], off offset:16
	s_mov_b32 s4, 0x10000
	s_waitcnt vmcnt(3)
	v_pk_fma_f32 v[106:107], v[106:107], v[142:143], v[148:149]
	v_pk_fma_f32 v[104:105], v[104:105], v[140:141], v[146:147]
	s_waitcnt vmcnt(2)
	v_pk_fma_f32 v[114:115], v[114:115], v[138:139], v[164:165]
	v_pk_fma_f32 v[112:113], v[112:113], v[136:137], v[162:163]
	s_waitcnt vmcnt(1)
	v_pk_fma_f32 v[66:67], v[66:67], v[134:135], v[174:175]
	v_pk_fma_f32 v[64:65], v[64:65], v[132:133], v[172:173]
	v_mul_f32_e32 v145, v105, v105
	v_mul_f32_e32 v146, v107, v107
	v_mul_f32_e32 v147, v113, v113
	v_mul_f32_e32 v148, v115, v115
	s_waitcnt vmcnt(0)
	v_pk_fma_f32 v[74:75], v[74:75], v[130:131], v[178:179]
	v_pk_fma_f32 v[72:73], v[72:73], v[128:129], v[176:177]
	v_mul_f32_e32 v149, v65, v65
	v_mul_f32_e32 v150, v67, v67
	v_fmac_f32_e32 v145, v104, v104
	v_fmac_f32_e32 v146, v106, v106
	v_fmac_f32_e32 v147, v112, v112
	v_fmac_f32_e32 v148, v114, v114
	v_mul_f32_e32 v151, v73, v73
	v_mul_f32_e32 v162, v75, v75
	v_fmac_f32_e32 v149, v64, v64
	v_fmac_f32_e32 v150, v66, v66
	v_add_f32_e32 v145, v145, v146
	v_add_f32_e32 v146, v147, v148
	v_fmac_f32_e32 v151, v72, v72
	v_fmac_f32_e32 v162, v74, v74
	v_add_f32_e32 v147, v149, v150
	v_add_f32_e32 v145, v145, v146
	v_add_f32_e32 v148, v151, v162
	v_add_f32_e32 v145, v145, v147
	v_add_f32_e32 v145, v145, v148
	ds_bpermute_b32 v146, v213, v145
	v_add_co_u32_e32 v216, vcc, s4, v166
	s_waitcnt lgkmcnt(0)
	v_add_f32_e32 v145, v145, v146
	ds_bpermute_b32 v146, v214, v145
	v_addc_co_u32_e32 v217, vcc, 0, v167, vcc
	s_and_saveexec_b64 s[4:5], s[0:1]
	v_readlane_b32 s24, v255, 38
	v_readlane_b32 s25, v255, 39
	s_mov_b64 s[34:35], s[60:61]
	s_cbranch_execz .LBB0_951
	s_waitcnt lgkmcnt(0)
	v_add_f32_e32 v145, v145, v146
	ds_write_b32 v144, v145 offset:256
; #define LAS __attribute__((address_space(3)))
; #define EF_LOAD(buf, g_) do { const float* xp_ = xi + (size_t)(((g_) >> 2) * 128 + ((g_) & 3) * 16) * DM; \
;             _Pragma("unroll") for (int bj = 0; bj < 2; ++bj) _Pragma("unroll") for (int n = 0; n < 2; ++n) xv[buf][bj][n] = *(const f32x4*)(xp_ + bj * 128 + n * 4); } while (0)
;     __device__ __forceinline__ void fused(Acc& acc, const pg8::Unit& u, int wr, int wc, int fr, int fq, LAS unsigned char* lds, int wid, int lane) const {
;     ...
;         LAS float* P = (LAS float*)lds;
;         LAS float* S = (LAS float*)(lds + 4096);
; #pragma unroll
;         for (int g_ = 0; g_ < 8; ++g_) {
;             EF_LOAD(0, g_);
;             float sq = 0.f;
; #pragma unroll
;             for (int bj = 0; bj < 2; ++bj)
; #pragma unroll
;                 for (int n = 0; n < 2; ++n) { const f32x4 xn = xv[0][bj][n] + gt[bj][n] * acc[g_ >> 2][bj][g_ & 3][n]; acc[g_ >> 2][bj][g_ & 3][n] = xn;
;                     if (MODE == 1) *(f32x4*)(xo + (size_t)((g_ >> 2) * 128 + (g_ & 3) * 16) * DM + bj * 128 + n * 4) = xn;
;                     sq += (xn[0] * xn[0] + xn[1] * xn[1]) + (xn[2] * xn[2] + xn[3] * xn[3]); }
;             sq += __shfl_xor(sq, 16); sq += __shfl_xor(sq, 32);
;             if (fq == 0) P[((g_ >> 2) * 128 + wr * 64 + (g_ & 3) * 16 + fr) * 4 + wc] = sq;
.LBB0_951:
	s_or_b64 exec, exec, s[4:5]
	v_add_co_u32_e32 v150, vcc, 0x20000, v168
	s_mov_b64 s[4:5], 0x20000
	s_nop 0
	v_addc_co_u32_e32 v151, vcc, 0, v169, vcc
	s_waitcnt lgkmcnt(0)
	global_load_dwordx4 v[146:149], v[150:151], off
	v_lshl_add_u64 v[162:163], v[168:169], 0, s[4:5]
	s_mov_b64 s[4:5], 0x20200
	global_load_dwordx4 v[162:165], v[162:163], off offset:16
	s_nop 0
	global_load_dwordx4 v[172:175], v[150:151], off offset:512
	v_lshl_add_u64 v[150:151], v[168:169], 0, s[4:5]
	global_load_dwordx4 v[176:179], v[150:151], off offset:16
	s_mov_b32 s4, 0x20000
	s_waitcnt vmcnt(3)
	v_pk_fma_f32 v[122:123], v[122:123], v[142:143], v[148:149]
	v_pk_fma_f32 v[120:121], v[120:121], v[140:141], v[146:147]
	s_waitcnt vmcnt(2)
	v_pk_fma_f32 v[126:127], v[126:127], v[138:139], v[164:165]
	v_pk_fma_f32 v[124:125], v[124:125], v[136:137], v[162:163]
	s_waitcnt vmcnt(1)
	v_pk_fma_f32 v[82:83], v[82:83], v[134:135], v[174:175]
	v_pk_fma_f32 v[80:81], v[80:81], v[132:133], v[172:173]
	v_mul_f32_e32 v145, v121, v121
	v_mul_f32_e32 v146, v123, v123
	v_mul_f32_e32 v147, v125, v125
	v_mul_f32_e32 v148, v127, v127
	s_waitcnt vmcnt(0)
	v_pk_fma_f32 v[90:91], v[90:91], v[130:131], v[178:179]
	v_pk_fma_f32 v[88:89], v[88:89], v[128:129], v[176:177]
	v_mul_f32_e32 v149, v81, v81
	v_mul_f32_e32 v150, v83, v83
	v_fmac_f32_e32 v145, v120, v120
	v_fmac_f32_e32 v146, v122, v122
	v_fmac_f32_e32 v147, v124, v124
	v_fmac_f32_e32 v148, v126, v126
	v_mul_f32_e32 v151, v89, v89
	v_mul_f32_e32 v162, v91, v91
	v_fmac_f32_e32 v149, v80, v80
	v_fmac_f32_e32 v150, v82, v82
	v_add_f32_e32 v145, v145, v146
	v_add_f32_e32 v146, v147, v148
	v_fmac_f32_e32 v151, v88, v88
	v_fmac_f32_e32 v162, v90, v90
	v_add_f32_e32 v147, v149, v150
	v_add_f32_e32 v145, v145, v146
	v_add_f32_e32 v148, v151, v162
	v_add_f32_e32 v145, v145, v147
	v_add_f32_e32 v145, v145, v148
	ds_bpermute_b32 v146, v213, v145
	v_add_co_u32_e32 v218, vcc, s4, v166
	s_waitcnt lgkmcnt(0)
	v_add_f32_e32 v145, v145, v146
	ds_bpermute_b32 v146, v214, v145
	v_addc_co_u32_e32 v219, vcc, 0, v167, vcc
	s_and_saveexec_b64 s[4:5], s[0:1]
	s_cbranch_execz .LBB0_953
	s_waitcnt lgkmcnt(0)
	v_add_f32_e32 v145, v145, v146
	ds_write_b32 v144, v145 offset:512
.LBB0_953:
	s_or_b64 exec, exec, s[4:5]
	v_add_co_u32_e32 v150, vcc, 0x30000, v168
	s_mov_b64 s[4:5], 0x30000
	s_nop 0
	v_addc_co_u32_e32 v151, vcc, 0, v169, vcc
	s_waitcnt lgkmcnt(0)
	global_load_dwordx4 v[146:149], v[150:151], off
	v_lshl_add_u64 v[162:163], v[168:169], 0, s[4:5]
	s_mov_b64 s[4:5], 0x30200
	global_load_dwordx4 v[162:165], v[162:163], off offset:16
	s_nop 0
	global_load_dwordx4 v[172:175], v[150:151], off offset:512
	v_lshl_add_u64 v[150:151], v[168:169], 0, s[4:5]
	global_load_dwordx4 v[176:179], v[150:151], off offset:16
	s_mov_b32 s4, 0x30000
	s_waitcnt vmcnt(3)
	v_pk_fma_f32 v[118:119], v[118:119], v[142:143], v[148:149]
	v_pk_fma_f32 v[116:117], v[116:117], v[140:141], v[146:147]
	s_waitcnt vmcnt(2)
	v_pk_fma_f32 v[110:111], v[110:111], v[138:139], v[164:165]
	v_pk_fma_f32 v[108:109], v[108:109], v[136:137], v[162:163]
	s_waitcnt vmcnt(1)
	v_pk_fma_f32 v[94:95], v[94:95], v[134:135], v[174:175]
	v_pk_fma_f32 v[92:93], v[92:93], v[132:133], v[172:173]
	v_mul_f32_e32 v145, v117, v117
	v_mul_f32_e32 v146, v119, v119
	v_mul_f32_e32 v147, v109, v109
	v_mul_f32_e32 v148, v111, v111
	s_waitcnt vmcnt(0)
	v_pk_fma_f32 v[86:87], v[86:87], v[130:131], v[178:179]
	v_pk_fma_f32 v[84:85], v[84:85], v[128:129], v[176:177]
	v_mul_f32_e32 v149, v93, v93
	v_mul_f32_e32 v150, v95, v95
	v_fmac_f32_e32 v145, v116, v116
	v_fmac_f32_e32 v146, v118, v118
	v_fmac_f32_e32 v147, v108, v108
	v_fmac_f32_e32 v148, v110, v110
	v_mul_f32_e32 v151, v85, v85
	v_mul_f32_e32 v162, v87, v87
	v_fmac_f32_e32 v149, v92, v92
	v_fmac_f32_e32 v150, v94, v94
	v_add_f32_e32 v145, v145, v146
	v_add_f32_e32 v146, v147, v148
	v_fmac_f32_e32 v151, v84, v84
	v_fmac_f32_e32 v162, v86, v86
	v_add_f32_e32 v147, v149, v150
	v_add_f32_e32 v145, v145, v146
	v_add_f32_e32 v148, v151, v162
	v_add_f32_e32 v145, v145, v147
	v_add_f32_e32 v145, v145, v148
	ds_bpermute_b32 v146, v213, v145
	v_add_co_u32_e32 v220, vcc, s4, v166
	s_waitcnt lgkmcnt(0)
	v_add_f32_e32 v145, v145, v146
	ds_bpermute_b32 v146, v214, v145
	v_addc_co_u32_e32 v221, vcc, 0, v167, vcc
	s_and_saveexec_b64 s[4:5], s[0:1]
	s_cbranch_execz .LBB0_955
	s_waitcnt lgkmcnt(0)
	v_add_f32_e32 v145, v145, v146
	ds_write_b32 v144, v145 offset:768
.LBB0_955:
	s_or_b64 exec, exec, s[4:5]
	v_add_co_u32_e32 v162, vcc, 0x80000, v168
	s_mov_b64 s[4:5], 0x80000
	s_nop 0
	v_addc_co_u32_e32 v163, vcc, 0, v169, vcc
	s_waitcnt lgkmcnt(0)
	global_load_dwordx4 v[144:147], v[162:163], off
	v_lshl_add_u64 v[148:149], v[168:169], 0, s[4:5]
	s_mov_b64 s[4:5], 0x80200
	global_load_dwordx4 v[148:151], v[148:149], off offset:16
	s_nop 0
	global_load_dwordx4 v[162:165], v[162:163], off offset:512
	v_lshl_add_u64 v[172:173], v[168:169], 0, s[4:5]
	global_load_dwordx4 v[172:175], v[172:173], off offset:16
	s_mov_b32 s4, 0x80000
	s_waitcnt vmcnt(3)
	v_pk_fma_f32 v[78:79], v[78:79], v[142:143], v[146:147]
	v_pk_fma_f32 v[76:77], v[76:77], v[140:141], v[144:145]
	s_waitcnt vmcnt(2)
	v_pk_fma_f32 v[70:71], v[70:71], v[138:139], v[150:151]
	v_pk_fma_f32 v[68:69], v[68:69], v[136:137], v[148:149]
	s_waitcnt vmcnt(1)
	v_pk_fma_f32 v[62:63], v[62:63], v[134:135], v[164:165]
	v_pk_fma_f32 v[60:61], v[60:61], v[132:133], v[162:163]
	v_mul_f32_e32 v144, v77, v77
	v_mul_f32_e32 v145, v79, v79
	v_mul_f32_e32 v146, v69, v69
	v_mul_f32_e32 v147, v71, v71
	s_waitcnt vmcnt(0)
	v_pk_fma_f32 v[58:59], v[58:59], v[130:131], v[174:175]
	v_pk_fma_f32 v[56:57], v[56:57], v[128:129], v[172:173]
	v_mul_f32_e32 v148, v61, v61
	v_mul_f32_e32 v149, v63, v63
	v_fmac_f32_e32 v144, v76, v76
	v_fmac_f32_e32 v145, v78, v78
	v_fmac_f32_e32 v146, v68, v68
	v_fmac_f32_e32 v147, v70, v70
	v_mul_f32_e32 v150, v57, v57
	v_mul_f32_e32 v151, v59, v59
	v_fmac_f32_e32 v148, v60, v60
	v_fmac_f32_e32 v149, v62, v62
	v_add_f32_e32 v144, v144, v145
	v_add_f32_e32 v145, v146, v147
	v_fmac_f32_e32 v150, v56, v56
	v_fmac_f32_e32 v151, v58, v58
	v_add_f32_e32 v146, v148, v149
	v_add_f32_e32 v144, v144, v145
	v_add_f32_e32 v147, v150, v151
	v_add_f32_e32 v144, v144, v146
	v_add_f32_e32 v144, v144, v147
	ds_bpermute_b32 v145, v213, v144
	v_add_co_u32_e32 v222, vcc, s4, v166
	s_waitcnt lgkmcnt(0)
	v_add_f32_e32 v144, v144, v145
	ds_bpermute_b32 v145, v214, v144
	v_addc_co_u32_e32 v223, vcc, 0, v167, vcc
	s_and_saveexec_b64 s[4:5], s[0:1]
	s_cbranch_execz .LBB0_957
	s_add_i32 s11, s7, 0x80
	v_or_b32_e32 v146, s11, v171
	v_lshl_add_u32 v146, v146, 4, s9
	s_waitcnt lgkmcnt(0)
	v_add_f32_e32 v144, v144, v145
	ds_write_b32 v146, v144
; #define LAS __attribute__((address_space(3)))
; #define EF_LOAD(buf, g_) do { const float* xp_ = xi + (size_t)(((g_) >> 2) * 128 + ((g_) & 3) * 16) * DM; \
;             _Pragma("unroll") for (int bj = 0; bj < 2; ++bj) _Pragma("unroll") for (int n = 0; n < 2; ++n) xv[buf][bj][n] = *(const f32x4*)(xp_ + bj * 128 + n * 4); } while (0)
;     __device__ __forceinline__ void fused(Acc& acc, const pg8::Unit& u, int wr, int wc, int fr, int fq, LAS unsigned char* lds, int wid, int lane) const {
;     ...
;         LAS float* P = (LAS float*)lds;
;         LAS float* S = (LAS float*)(lds + 4096);
; #pragma unroll
;         for (int g_ = 0; g_ < 8; ++g_) {
;             EF_LOAD(0, g_);
;             float sq = 0.f;
; #pragma unroll
;             for (int bj = 0; bj < 2; ++bj)
; #pragma unroll
;                 for (int n = 0; n < 2; ++n) { const f32x4 xn = xv[0][bj][n] + gt[bj][n] * acc[g_ >> 2][bj][g_ & 3][n]; acc[g_ >> 2][bj][g_ & 3][n] = xn;
;                     if (MODE == 1) *(f32x4*)(xo + (size_t)((g_ >> 2) * 128 + (g_ & 3) * 16) * DM + bj * 128 + n * 4) = xn;
;                     sq += (xn[0] * xn[0] + xn[1] * xn[1]) + (xn[2] * xn[2] + xn[3] * xn[3]); }
;             sq += __shfl_xor(sq, 16); sq += __shfl_xor(sq, 32);
;             if (fq == 0) P[((g_ >> 2) * 128 + wr * 64 + (g_ & 3) * 16 + fr) * 4 + wc] = sq;
.LBB0_957:
	s_or_b64 exec, exec, s[4:5]
	v_add_co_u32_e32 v162, vcc, 0x90000, v168
	s_mov_b64 s[4:5], 0x90000
	s_nop 0
	v_addc_co_u32_e32 v163, vcc, 0, v169, vcc
	s_waitcnt lgkmcnt(0)
	global_load_dwordx4 v[144:147], v[162:163], off
	v_lshl_add_u64 v[148:149], v[168:169], 0, s[4:5]
	s_mov_b64 s[4:5], 0x90200
	global_load_dwordx4 v[148:151], v[148:149], off offset:16
	s_nop 0
	global_load_dwordx4 v[162:165], v[162:163], off offset:512
	v_lshl_add_u64 v[172:173], v[168:169], 0, s[4:5]
	global_load_dwordx4 v[172:175], v[172:173], off offset:16
	s_mov_b32 s4, 0x90000
	s_waitcnt vmcnt(3)
	v_pk_fma_f32 v[46:47], v[46:47], v[142:143], v[146:147]
	v_pk_fma_f32 v[44:45], v[44:45], v[140:141], v[144:145]
	s_waitcnt vmcnt(2)
	v_pk_fma_f32 v[42:43], v[42:43], v[138:139], v[150:151]
	v_pk_fma_f32 v[40:41], v[40:41], v[136:137], v[148:149]
	s_waitcnt vmcnt(1)
	v_pk_fma_f32 v[38:39], v[38:39], v[134:135], v[164:165]
	v_pk_fma_f32 v[36:37], v[36:37], v[132:133], v[162:163]
	v_mul_f32_e32 v144, v45, v45
	v_mul_f32_e32 v145, v47, v47
	v_mul_f32_e32 v146, v41, v41
	v_mul_f32_e32 v147, v43, v43
	s_waitcnt vmcnt(0)
	v_pk_fma_f32 v[34:35], v[34:35], v[130:131], v[174:175]
	v_pk_fma_f32 v[32:33], v[32:33], v[128:129], v[172:173]
	v_mul_f32_e32 v148, v37, v37
	v_mul_f32_e32 v149, v39, v39
	v_fmac_f32_e32 v144, v44, v44
	v_fmac_f32_e32 v145, v46, v46
	v_fmac_f32_e32 v146, v40, v40
	v_fmac_f32_e32 v147, v42, v42
	v_mul_f32_e32 v150, v33, v33
	v_mul_f32_e32 v151, v35, v35
	v_fmac_f32_e32 v148, v36, v36
	v_fmac_f32_e32 v149, v38, v38
	v_add_f32_e32 v144, v144, v145
	v_add_f32_e32 v145, v146, v147
	v_fmac_f32_e32 v150, v32, v32
	v_fmac_f32_e32 v151, v34, v34
	v_add_f32_e32 v146, v148, v149
	v_add_f32_e32 v144, v144, v145
	v_add_f32_e32 v147, v150, v151
	v_add_f32_e32 v144, v144, v146
	v_add_f32_e32 v144, v144, v147
	ds_bpermute_b32 v145, v213, v144
	v_add_co_u32_e32 v224, vcc, s4, v166
	s_waitcnt lgkmcnt(0)
	v_add_f32_e32 v144, v144, v145
	ds_bpermute_b32 v145, v214, v144
	v_addc_co_u32_e32 v225, vcc, 0, v167, vcc
	s_and_saveexec_b64 s[4:5], s[0:1]
	s_cbranch_execz .LBB0_959
	s_add_i32 s11, s7, 0x90
	v_or_b32_e32 v146, s11, v171
	v_lshl_add_u32 v146, v146, 4, s9
	s_waitcnt lgkmcnt(0)
	v_add_f32_e32 v144, v144, v145
	ds_write_b32 v146, v144
.LBB0_959:
	s_or_b64 exec, exec, s[4:5]
	v_add_co_u32_e32 v162, vcc, 0xa0000, v168
	s_mov_b64 s[4:5], 0xa0000
	s_nop 0
	v_addc_co_u32_e32 v163, vcc, 0, v169, vcc
	v_lshl_add_u64 v[148:149], v[168:169], 0, s[4:5]
	s_mov_b64 s[4:5], 0xa0200
	s_waitcnt lgkmcnt(0)
	global_load_dwordx4 v[144:147], v[162:163], off
	v_lshl_add_u64 v[172:173], v[168:169], 0, s[4:5]
	global_load_dwordx4 v[148:151], v[148:149], off offset:16
	s_nop 0
	global_load_dwordx4 v[162:165], v[162:163], off offset:512
	s_mov_b32 s4, 0xa0000
	global_load_dwordx4 v[172:175], v[172:173], off offset:16
	s_waitcnt vmcnt(3)
	v_pk_fma_f32 v[146:147], v[30:31], v[142:143], v[146:147]
	v_pk_fma_f32 v[144:145], v[28:29], v[140:141], v[144:145]
	s_waitcnt vmcnt(2)
	v_pk_fma_f32 v[150:151], v[26:27], v[138:139], v[150:151]
	v_pk_fma_f32 v[148:149], v[24:25], v[136:137], v[148:149]
	s_waitcnt vmcnt(1)
	v_pk_fma_f32 v[26:27], v[22:23], v[134:135], v[164:165]
	v_pk_fma_f32 v[24:25], v[20:21], v[132:133], v[162:163]
	s_waitcnt vmcnt(0)
	v_pk_fma_f32 v[30:31], v[18:19], v[130:131], v[174:175]
	v_pk_fma_f32 v[28:29], v[16:17], v[128:129], v[172:173]
	v_mul_f32_e32 v16, v145, v145
	v_mul_f32_e32 v17, v147, v147
	v_mul_f32_e32 v18, v149, v149
	v_mul_f32_e32 v19, v151, v151
	v_mul_f32_e32 v20, v25, v25
	v_mul_f32_e32 v21, v27, v27
	v_fmac_f32_e32 v16, v144, v144
	v_fmac_f32_e32 v17, v146, v146
	v_fmac_f32_e32 v18, v148, v148
	v_fmac_f32_e32 v19, v150, v150
	v_mul_f32_e32 v22, v29, v29
	v_mul_f32_e32 v23, v31, v31
	v_fmac_f32_e32 v20, v24, v24
	v_fmac_f32_e32 v21, v26, v26
	v_add_f32_e32 v16, v16, v17
	v_add_f32_e32 v17, v18, v19
	v_fmac_f32_e32 v22, v28, v28
	v_fmac_f32_e32 v23, v30, v30
	v_add_f32_e32 v18, v20, v21
	v_add_f32_e32 v16, v16, v17
	v_add_f32_e32 v19, v22, v23
	v_add_f32_e32 v16, v16, v18
	v_add_f32_e32 v16, v16, v19
	ds_bpermute_b32 v17, v213, v16
	v_add_co_u32_e32 v226, vcc, s4, v166
	s_waitcnt lgkmcnt(0)
	v_add_f32_e32 v16, v16, v17
	ds_bpermute_b32 v17, v214, v16
	v_addc_co_u32_e32 v227, vcc, 0, v167, vcc
	s_and_saveexec_b64 s[4:5], s[0:1]
	s_cbranch_execz .LBB0_961
	s_add_i32 s11, s7, 0xa0
	v_or_b32_e32 v18, s11, v171
	v_lshl_add_u32 v18, v18, 4, s9
	s_waitcnt lgkmcnt(0)
	v_add_f32_e32 v16, v16, v17
	ds_write_b32 v18, v16
; #define LAS __attribute__((address_space(3)))
; #define EF_LOAD(buf, g_) do { const float* xp_ = xi + (size_t)(((g_) >> 2) * 128 + ((g_) & 3) * 16) * DM; \
;             _Pragma("unroll") for (int bj = 0; bj < 2; ++bj) _Pragma("unroll") for (int n = 0; n < 2; ++n) xv[buf][bj][n] = *(const f32x4*)(xp_ + bj * 128 + n * 4); } while (0)
;     __device__ __forceinline__ void fused(Acc& acc, const pg8::Unit& u, int wr, int wc, int fr, int fq, LAS unsigned char* lds, int wid, int lane) const {
;     ...
;         LAS float* P = (LAS float*)lds;
;         LAS float* S = (LAS float*)(lds + 4096);
; #pragma unroll
;         for (int g_ = 0; g_ < 8; ++g_) {
;             EF_LOAD(0, g_);
;             float sq = 0.f;
; #pragma unroll
;             for (int bj = 0; bj < 2; ++bj)
; #pragma unroll
;                 for (int n = 0; n < 2; ++n) { const f32x4 xn = xv[0][bj][n] + gt[bj][n] * acc[g_ >> 2][bj][g_ & 3][n]; acc[g_ >> 2][bj][g_ & 3][n] = xn;
;                     if (MODE == 1) *(f32x4*)(xo + (size_t)((g_ >> 2) * 128 + (g_ & 3) * 16) * DM + bj * 128 + n * 4) = xn;
;                     sq += (xn[0] * xn[0] + xn[1] * xn[1]) + (xn[2] * xn[2] + xn[3] * xn[3]); }
;             sq += __shfl_xor(sq, 16); sq += __shfl_xor(sq, 32);
;             if (fq == 0) P[((g_ >> 2) * 128 + wr * 64 + (g_ & 3) * 16 + fr) * 4 + wc] = sq;
.LBB0_961:
	s_or_b64 exec, exec, s[4:5]
	v_add_co_u32_e32 v162, vcc, 0xb0000, v168
	s_mov_b64 s[4:5], 0xb0000
	s_nop 0
	v_addc_co_u32_e32 v163, vcc, 0, v169, vcc
	s_waitcnt lgkmcnt(0)
	global_load_dwordx4 v[16:19], v[162:163], off
	v_lshl_add_u64 v[20:21], v[168:169], 0, s[4:5]
	s_mov_b64 s[4:5], 0xb0200
	global_load_dwordx4 v[20:23], v[20:21], off offset:16
	s_nop 0
	global_load_dwordx4 v[162:165], v[162:163], off offset:512
	v_lshl_add_u64 v[168:169], v[168:169], 0, s[4:5]
	global_load_dwordx4 v[172:175], v[168:169], off offset:16
	s_mov_b32 s4, 0xb0000
	s_waitcnt vmcnt(3)
	v_pk_fma_f32 v[14:15], v[14:15], v[142:143], v[18:19]
	v_pk_fma_f32 v[12:13], v[12:13], v[140:141], v[16:17]
	s_waitcnt vmcnt(2)
	v_pk_fma_f32 v[10:11], v[10:11], v[138:139], v[22:23]
	v_pk_fma_f32 v[8:9], v[8:9], v[136:137], v[20:21]
	s_waitcnt vmcnt(1)
	v_pk_fma_f32 v[2:3], v[2:3], v[134:135], v[164:165]
	v_pk_fma_f32 v[0:1], v[0:1], v[132:133], v[162:163]
	v_mul_f32_e32 v16, v13, v13
	v_mul_f32_e32 v17, v15, v15
	v_mul_f32_e32 v18, v9, v9
	v_mul_f32_e32 v19, v11, v11
	s_waitcnt vmcnt(0)
	v_pk_fma_f32 v[6:7], v[6:7], v[130:131], v[174:175]
	v_pk_fma_f32 v[4:5], v[4:5], v[128:129], v[172:173]
	v_mul_f32_e32 v20, v1, v1
	v_mul_f32_e32 v21, v3, v3
	v_fmac_f32_e32 v16, v12, v12
	v_fmac_f32_e32 v17, v14, v14
	v_fmac_f32_e32 v18, v8, v8
	v_fmac_f32_e32 v19, v10, v10
	v_mul_f32_e32 v22, v5, v5
	v_mul_f32_e32 v23, v7, v7
	v_fmac_f32_e32 v20, v0, v0
	v_fmac_f32_e32 v21, v2, v2
	v_add_f32_e32 v16, v16, v17
	v_add_f32_e32 v17, v18, v19
	v_fmac_f32_e32 v22, v4, v4
	v_fmac_f32_e32 v23, v6, v6
	v_add_f32_e32 v18, v20, v21
	v_add_f32_e32 v16, v16, v17
	v_add_f32_e32 v19, v22, v23
	v_add_f32_e32 v16, v16, v18
	v_add_f32_e32 v16, v16, v19
	ds_bpermute_b32 v17, v213, v16
	v_add_co_u32_e32 v18, vcc, s4, v166
	s_waitcnt lgkmcnt(0)
	v_add_f32_e32 v16, v16, v17
	ds_bpermute_b32 v17, v214, v16
	v_addc_co_u32_e32 v19, vcc, 0, v167, vcc
	global_store_dwordx4 v[166:167], v[96:99], off
	global_store_dwordx4 v[166:167], v[100:103], off offset:16
	global_store_dwordx4 v[166:167], v[48:51], off offset:512
	global_store_dwordx4 v[166:167], v[52:55], off offset:528
	global_store_dwordx4 v[216:217], v[104:107], off
	global_store_dwordx4 v[216:217], v[112:115], off offset:16
	global_store_dwordx4 v[216:217], v[64:67], off offset:512
	global_store_dwordx4 v[216:217], v[72:75], off offset:528
	global_store_dwordx4 v[218:219], v[120:123], off
	global_store_dwordx4 v[218:219], v[124:127], off offset:16
	global_store_dwordx4 v[218:219], v[80:83], off offset:512
	global_store_dwordx4 v[218:219], v[88:91], off offset:528
	global_store_dwordx4 v[220:221], v[116:119], off
	global_store_dwordx4 v[220:221], v[108:111], off offset:16
	global_store_dwordx4 v[220:221], v[92:95], off offset:512
	global_store_dwordx4 v[220:221], v[84:87], off offset:528
	global_store_dwordx4 v[222:223], v[76:79], off
	global_store_dwordx4 v[222:223], v[68:71], off offset:16
	global_store_dwordx4 v[222:223], v[60:63], off offset:512
	global_store_dwordx4 v[222:223], v[56:59], off offset:528
	global_store_dwordx4 v[224:225], v[44:47], off
	global_store_dwordx4 v[224:225], v[40:43], off offset:16
	global_store_dwordx4 v[224:225], v[36:39], off offset:512
	global_store_dwordx4 v[224:225], v[32:35], off offset:528
	global_store_dwordx4 v[226:227], v[144:147], off
	global_store_dwordx4 v[226:227], v[148:151], off offset:16
	global_store_dwordx4 v[226:227], v[24:27], off offset:512
	global_store_dwordx4 v[226:227], v[28:31], off offset:528
	global_store_dwordx4 v[18:19], v[12:15], off
	global_store_dwordx4 v[18:19], v[8:11], off offset:16
	global_store_dwordx4 v[18:19], v[0:3], off offset:512
	global_store_dwordx4 v[18:19], v[4:7], off offset:528
	s_and_saveexec_b64 s[4:5], s[0:1]
	s_cbranch_execz .LBB0_963
	s_add_i32 s0, s7, 0xb0
	v_or_b32_e32 v18, s0, v171
	v_lshl_add_u32 v18, v18, 4, s9
	s_waitcnt lgkmcnt(0)
	v_add_f32_e32 v16, v16, v17
	ds_write_b32 v18, v16

; #define LAS __attribute__((address_space(3)))
; #define EF_LOAD(buf, g_) do { const float* xp_ = xi + (size_t)(((g_) >> 2) * 128 + ((g_) & 3) * 16) * DM; \
;             _Pragma("unroll") for (int bj = 0; bj < 2; ++bj) _Pragma("unroll") for (int n = 0; n < 2; ++n) xv[buf][bj][n] = *(const f32x4*)(xp_ + bj * 128 + n * 4); } while (0)
;     __device__ __forceinline__ void fused(Acc& acc, const pg8::Unit& u, int wr, int wc, int fr, int fq, LAS unsigned char* lds, int wid, int lane) const {
;         const int tile0 = u.pm * 256, colb = u.pn * 256 + wc * 32 + 8 * fq, rloc = wr * 64 + fr;
;         const float* xi = xin + (size_t)(tile0 + rloc) * DM + colb;
;         float* xo = out + (size_t)(tile0 + rloc) * DM + colb;
;         const float* gp = mod + (tile0 >> 11) * 6144 + goff + colb;
;         f32x4 gt[2][2];
; #pragma unroll
;         for (int bj = 0; bj < 2; ++bj)
; #pragma unroll
;             for (int n = 0; n < 2; ++n) gt[bj][n] = *(const f32x4*)(gp + bj * 128 + n * 4);
;         f32x4 xv[1][2][2];
;     ...
;         LAS float* P = (LAS float*)lds;
;         LAS float* S = (LAS float*)(lds + 4096);
; #pragma unroll
;         for (int g_ = 0; g_ < 8; ++g_) {
;             EF_LOAD(0, g_);
;             float sq = 0.f;
; #pragma unroll
;             for (int bj = 0; bj < 2; ++bj)
; #pragma unroll
;                 for (int n = 0; n < 2; ++n) { const f32x4 xn = xv[0][bj][n] + gt[bj][n] * acc[g_ >> 2][bj][g_ & 3][n]; acc[g_ >> 2][bj][g_ & 3][n] = xn;
;                     if (MODE == 1) *(f32x4*)(xo + (size_t)((g_ >> 2) * 128 + (g_ & 3) * 16) * DM + bj * 128 + n * 4) = xn;
;                     sq += (xn[0] * xn[0] + xn[1] * xn[1]) + (xn[2] * xn[2] + xn[3] * xn[3]); }
;             sq += __shfl_xor(sq, 16); sq += __shfl_xor(sq, 32);
;             if (fq == 0) P[((g_ >> 2) * 128 + wr * 64 + (g_ & 3) * 16 + fr) * 4 + wc] = sq;
.LBB0_1051:
	s_lshr_b32 s12, s96, 3
	s_mulk_i32 s12, 0x1800
	s_ashr_i32 s13, s12, 31
	s_lshl_b64 s[12:13], s[12:13], 2
	s_add_u32 s12, s48, s12
	s_addc_u32 s13, s49, s13
	v_lshlrev_b64 v[174:175], 2, v[172:173]
	v_add_u32_e32 v176, s34, v158
	v_lshl_add_u64 v[170:171], s[12:13], 0, v[174:175]
	v_ashrrev_i32_e32 v177, 31, v176
	v_add_co_u32_e32 v128, vcc, s21, v170
	v_readlane_b32 s12, v255, 28
	v_lshlrev_b64 v[178:179], 12, v[176:177]
	v_addc_co_u32_e32 v129, vcc, 0, v171, vcc
	v_readlane_b32 s13, v255, 29
	global_load_dwordx4 v[140:143], v[128:129], off
	v_readlane_b32 s68, v252, 0
	v_lshl_add_u64 v[128:129], s[12:13], 0, v[178:179]
	v_lshl_add_u64 v[180:181], v[128:129], 0, v[174:175]
	global_load_dwordx4 v[144:147], v[180:181], off offset:16
	global_load_dwordx4 v[148:151], v[180:181], off
	s_mov_b64 s[12:13], 0x2000
	v_lshl_add_u64 v[128:129], v[170:171], 0, s[12:13]
	global_load_dwordx4 v[136:139], v[128:129], off offset:16
	global_load_dwordx4 v[132:135], v[128:129], off offset:512
	global_load_dwordx4 v[162:165], v[180:181], off offset:512
	global_load_dwordx4 v[200:203], v[180:181], off offset:528
	s_nop 0
	global_load_dwordx4 v[128:131], v[128:129], off offset:528
	v_readlane_b32 s70, v252, 2
	v_readlane_b32 s71, v252, 3
	v_readlane_b32 s69, v252, 1
	v_readlane_b32 s72, v252, 4
	v_readlane_b32 s73, v252, 5
	v_readlane_b32 s74, v252, 6
	v_readlane_b32 s75, v252, 7
	s_waitcnt vmcnt(0)
	v_pk_fma_f32 v[118:119], v[118:119], v[138:139], v[146:147]
	v_pk_fma_f32 v[114:115], v[114:115], v[142:143], v[150:151]
	v_pk_fma_f32 v[112:113], v[112:113], v[140:141], v[148:149]
	v_pk_fma_f32 v[116:117], v[116:117], v[136:137], v[144:145]
	v_pk_fma_f32 v[66:67], v[66:67], v[134:135], v[164:165]
	v_pk_fma_f32 v[64:65], v[64:65], v[132:133], v[162:163]
	v_mul_f32_e32 v144, v113, v113
	v_mul_f32_e32 v145, v115, v115
	v_mul_f32_e32 v146, v117, v117
	v_mul_f32_e32 v147, v119, v119
	v_pk_fma_f32 v[70:71], v[70:71], v[130:131], v[202:203]
	v_pk_fma_f32 v[68:69], v[68:69], v[128:129], v[200:201]
	v_mul_f32_e32 v148, v65, v65
	v_mul_f32_e32 v149, v67, v67
	v_fmac_f32_e32 v144, v112, v112
	v_fmac_f32_e32 v145, v114, v114
	v_fmac_f32_e32 v146, v116, v116
	v_fmac_f32_e32 v147, v118, v118
	v_mul_f32_e32 v150, v69, v69
	v_mul_f32_e32 v151, v71, v71
	v_fmac_f32_e32 v148, v64, v64
	v_fmac_f32_e32 v149, v66, v66
	v_add_f32_e32 v144, v144, v145
	v_add_f32_e32 v145, v146, v147
	v_fmac_f32_e32 v150, v68, v68
	v_fmac_f32_e32 v151, v70, v70
	v_add_f32_e32 v146, v148, v149
	v_add_f32_e32 v144, v144, v145
	v_add_f32_e32 v144, v144, v146
	v_add_f32_e32 v145, v150, v151
	v_add_f32_e32 v146, v144, v145
	ds_bpermute_b32 v147, v213, v146
	v_lshl_add_u64 v[144:145], s[70:71], 0, v[178:179]
	v_lshl_add_u64 v[178:179], v[144:145], 0, v[174:175]
	s_waitcnt lgkmcnt(0)
	v_add_f32_e32 v144, v146, v147
	ds_bpermute_b32 v145, v214, v144
	s_and_saveexec_b64 s[12:13], s[4:5]
	s_cbranch_execz .LBB0_1053
	s_waitcnt lgkmcnt(0)
	v_add_f32_e32 v144, v144, v145
	ds_write_b32 v215, v144
.LBB0_1053:
	s_or_b64 exec, exec, s[12:13]
	v_add_co_u32_e32 v162, vcc, 0x10000, v180
	v_lshl_add_u64 v[148:149], v[180:181], 0, s[88:89]
	s_nop 0
	v_addc_co_u32_e32 v163, vcc, 0, v181, vcc
	s_waitcnt lgkmcnt(0)
	global_load_dwordx4 v[144:147], v[162:163], off
	s_mov_b64 s[12:13], 0x10200
	global_load_dwordx4 v[148:151], v[148:149], off offset:16
	s_nop 0
	global_load_dwordx4 v[162:165], v[162:163], off offset:512
	v_lshl_add_u64 v[200:201], v[180:181], 0, s[12:13]
	global_load_dwordx4 v[200:203], v[200:201], off offset:16
	s_mov_b32 s12, 0x10000
	s_waitcnt vmcnt(3)
	v_pk_fma_f32 v[122:123], v[122:123], v[142:143], v[146:147]
	v_pk_fma_f32 v[120:121], v[120:121], v[140:141], v[144:145]
	s_waitcnt vmcnt(2)
	v_pk_fma_f32 v[126:127], v[126:127], v[138:139], v[150:151]
	v_pk_fma_f32 v[124:125], v[124:125], v[136:137], v[148:149]
	s_waitcnt vmcnt(1)
	v_pk_fma_f32 v[86:87], v[86:87], v[134:135], v[164:165]
	v_pk_fma_f32 v[84:85], v[84:85], v[132:133], v[162:163]
	v_mul_f32_e32 v144, v121, v121
	v_mul_f32_e32 v145, v123, v123
	v_mul_f32_e32 v146, v125, v125
	v_mul_f32_e32 v147, v127, v127
	s_waitcnt vmcnt(0)
	v_pk_fma_f32 v[94:95], v[94:95], v[130:131], v[202:203]
	v_pk_fma_f32 v[92:93], v[92:93], v[128:129], v[200:201]
	v_mul_f32_e32 v148, v85, v85
	v_mul_f32_e32 v149, v87, v87
	v_fmac_f32_e32 v144, v120, v120
	v_fmac_f32_e32 v145, v122, v122
	v_fmac_f32_e32 v146, v124, v124
	v_fmac_f32_e32 v147, v126, v126
	v_mul_f32_e32 v150, v93, v93
	v_mul_f32_e32 v151, v95, v95
	v_fmac_f32_e32 v148, v84, v84
	v_fmac_f32_e32 v149, v86, v86
	v_add_f32_e32 v144, v144, v145
	v_add_f32_e32 v145, v146, v147
	v_fmac_f32_e32 v150, v92, v92
	v_fmac_f32_e32 v151, v94, v94
	v_add_f32_e32 v146, v148, v149
	v_add_f32_e32 v144, v144, v145
	v_add_f32_e32 v147, v150, v151
	v_add_f32_e32 v144, v144, v146
	v_add_f32_e32 v144, v144, v147
	ds_bpermute_b32 v145, v213, v144
	v_add_co_u32_e32 v216, vcc, s12, v178
	s_waitcnt lgkmcnt(0)
	v_add_f32_e32 v144, v144, v145
	ds_bpermute_b32 v145, v214, v144
	v_addc_co_u32_e32 v217, vcc, 0, v179, vcc
	s_and_saveexec_b64 s[12:13], s[4:5]
	s_cbranch_execz .LBB0_1055
	s_waitcnt lgkmcnt(0)
	v_add_f32_e32 v144, v144, v145
	ds_write_b32 v215, v144 offset:256
; #define LAS __attribute__((address_space(3)))
; #define EF_LOAD(buf, g_) do { const float* xp_ = xi + (size_t)(((g_) >> 2) * 128 + ((g_) & 3) * 16) * DM; \
;             _Pragma("unroll") for (int bj = 0; bj < 2; ++bj) _Pragma("unroll") for (int n = 0; n < 2; ++n) xv[buf][bj][n] = *(const f32x4*)(xp_ + bj * 128 + n * 4); } while (0)
;     __device__ __forceinline__ void fused(Acc& acc, const pg8::Unit& u, int wr, int wc, int fr, int fq, LAS unsigned char* lds, int wid, int lane) const {
;     ...
;         LAS float* P = (LAS float*)lds;
;         LAS float* S = (LAS float*)(lds + 4096);
; #pragma unroll
;         for (int g_ = 0; g_ < 8; ++g_) {
;             EF_LOAD(0, g_);
;             float sq = 0.f;
; #pragma unroll
;             for (int bj = 0; bj < 2; ++bj)
; #pragma unroll
;                 for (int n = 0; n < 2; ++n) { const f32x4 xn = xv[0][bj][n] + gt[bj][n] * acc[g_ >> 2][bj][g_ & 3][n]; acc[g_ >> 2][bj][g_ & 3][n] = xn;
;                     if (MODE == 1) *(f32x4*)(xo + (size_t)((g_ >> 2) * 128 + (g_ & 3) * 16) * DM + bj * 128 + n * 4) = xn;
;                     sq += (xn[0] * xn[0] + xn[1] * xn[1]) + (xn[2] * xn[2] + xn[3] * xn[3]); }
;             sq += __shfl_xor(sq, 16); sq += __shfl_xor(sq, 32);
;             if (fq == 0) P[((g_ >> 2) * 128 + wr * 64 + (g_ & 3) * 16 + fr) * 4 + wc] = sq;
.LBB0_1055:
	s_or_b64 exec, exec, s[12:13]
	v_add_co_u32_e32 v162, vcc, 0x20000, v180
	s_mov_b64 s[12:13], 0x20000
	s_nop 0
	v_addc_co_u32_e32 v163, vcc, 0, v181, vcc
	s_waitcnt lgkmcnt(0)
	global_load_dwordx4 v[144:147], v[162:163], off
	v_lshl_add_u64 v[148:149], v[180:181], 0, s[12:13]
	s_mov_b64 s[12:13], 0x20200
	global_load_dwordx4 v[148:151], v[148:149], off offset:16
	s_nop 0
	global_load_dwordx4 v[162:165], v[162:163], off offset:512
	v_lshl_add_u64 v[200:201], v[180:181], 0, s[12:13]
	global_load_dwordx4 v[200:203], v[200:201], off offset:16
	s_mov_b32 s12, 0x20000
	s_waitcnt vmcnt(3)
	v_pk_fma_f32 v[110:111], v[110:111], v[142:143], v[146:147]
	v_pk_fma_f32 v[108:109], v[108:109], v[140:141], v[144:145]
	s_waitcnt vmcnt(2)
	v_pk_fma_f32 v[106:107], v[106:107], v[138:139], v[150:151]
	v_pk_fma_f32 v[104:105], v[104:105], v[136:137], v[148:149]
	s_waitcnt vmcnt(1)
	v_pk_fma_f32 v[102:103], v[102:103], v[134:135], v[164:165]
	v_pk_fma_f32 v[100:101], v[100:101], v[132:133], v[162:163]
	v_mul_f32_e32 v144, v109, v109
	v_mul_f32_e32 v145, v111, v111
	v_mul_f32_e32 v146, v105, v105
	v_mul_f32_e32 v147, v107, v107
	s_waitcnt vmcnt(0)
	v_pk_fma_f32 v[98:99], v[98:99], v[130:131], v[202:203]
	v_pk_fma_f32 v[96:97], v[96:97], v[128:129], v[200:201]
	v_mul_f32_e32 v148, v101, v101
	v_mul_f32_e32 v149, v103, v103
	v_fmac_f32_e32 v144, v108, v108
	v_fmac_f32_e32 v145, v110, v110
	v_fmac_f32_e32 v146, v104, v104
	v_fmac_f32_e32 v147, v106, v106
	v_mul_f32_e32 v150, v97, v97
	v_mul_f32_e32 v151, v99, v99
	v_fmac_f32_e32 v148, v100, v100
	v_fmac_f32_e32 v149, v102, v102
	v_add_f32_e32 v144, v144, v145
	v_add_f32_e32 v145, v146, v147
	v_fmac_f32_e32 v150, v96, v96
	v_fmac_f32_e32 v151, v98, v98
	v_add_f32_e32 v146, v148, v149
	v_add_f32_e32 v144, v144, v145
	v_add_f32_e32 v147, v150, v151
	v_add_f32_e32 v144, v144, v146
	v_add_f32_e32 v144, v144, v147
	ds_bpermute_b32 v145, v213, v144
	v_add_co_u32_e32 v218, vcc, s12, v178
	s_waitcnt lgkmcnt(0)
	v_add_f32_e32 v144, v144, v145
	ds_bpermute_b32 v145, v214, v144
	v_addc_co_u32_e32 v219, vcc, 0, v179, vcc
	s_and_saveexec_b64 s[12:13], s[4:5]
	v_readlane_b32 s72, v255, 36
	v_readlane_b32 s73, v255, 37
	s_cbranch_execz .LBB0_1057
	s_waitcnt lgkmcnt(0)
	v_add_f32_e32 v144, v144, v145
	ds_write_b32 v215, v144 offset:512
.LBB0_1057:
	s_or_b64 exec, exec, s[12:13]
	v_add_co_u32_e32 v162, vcc, 0x30000, v180
	s_mov_b64 s[12:13], 0x30000
	s_nop 0
	v_addc_co_u32_e32 v163, vcc, 0, v181, vcc
	s_waitcnt lgkmcnt(0)
	global_load_dwordx4 v[144:147], v[162:163], off
	v_lshl_add_u64 v[148:149], v[180:181], 0, s[12:13]
	s_mov_b64 s[12:13], 0x30200
	global_load_dwordx4 v[148:151], v[148:149], off offset:16
	s_nop 0
	global_load_dwordx4 v[162:165], v[162:163], off offset:512
	v_lshl_add_u64 v[200:201], v[180:181], 0, s[12:13]
	global_load_dwordx4 v[200:203], v[200:201], off offset:16
	s_mov_b32 s12, 0x30000
	s_waitcnt vmcnt(3)
	v_pk_fma_f32 v[90:91], v[90:91], v[142:143], v[146:147]
	v_pk_fma_f32 v[88:89], v[88:89], v[140:141], v[144:145]
	s_waitcnt vmcnt(2)
	v_pk_fma_f32 v[82:83], v[82:83], v[138:139], v[150:151]
	v_pk_fma_f32 v[80:81], v[80:81], v[136:137], v[148:149]
	s_waitcnt vmcnt(1)
	v_pk_fma_f32 v[78:79], v[78:79], v[134:135], v[164:165]
	v_pk_fma_f32 v[76:77], v[76:77], v[132:133], v[162:163]
	v_mul_f32_e32 v144, v89, v89
	v_mul_f32_e32 v145, v91, v91
	v_mul_f32_e32 v146, v81, v81
	v_mul_f32_e32 v147, v83, v83
	s_waitcnt vmcnt(0)
	v_pk_fma_f32 v[74:75], v[74:75], v[130:131], v[202:203]
	v_pk_fma_f32 v[72:73], v[72:73], v[128:129], v[200:201]
	v_mul_f32_e32 v148, v77, v77
	v_mul_f32_e32 v149, v79, v79
	v_fmac_f32_e32 v144, v88, v88
	v_fmac_f32_e32 v145, v90, v90
	v_fmac_f32_e32 v146, v80, v80
	v_fmac_f32_e32 v147, v82, v82
	v_mul_f32_e32 v150, v73, v73
	v_mul_f32_e32 v151, v75, v75
	v_fmac_f32_e32 v148, v76, v76
	v_fmac_f32_e32 v149, v78, v78
	v_add_f32_e32 v144, v144, v145
	v_add_f32_e32 v145, v146, v147
	v_fmac_f32_e32 v150, v72, v72
	v_fmac_f32_e32 v151, v74, v74
	v_add_f32_e32 v146, v148, v149
	v_add_f32_e32 v144, v144, v145
	v_add_f32_e32 v147, v150, v151
	v_add_f32_e32 v144, v144, v146
	v_add_f32_e32 v144, v144, v147
	ds_bpermute_b32 v145, v213, v144
	v_add_co_u32_e32 v220, vcc, s12, v178
	s_waitcnt lgkmcnt(0)
	v_add_f32_e32 v144, v144, v145
	ds_bpermute_b32 v145, v214, v144
	v_addc_co_u32_e32 v221, vcc, 0, v179, vcc
	s_and_saveexec_b64 s[12:13], s[4:5]
	s_cbranch_execz .LBB0_1059
	s_waitcnt lgkmcnt(0)
	v_add_f32_e32 v144, v144, v145
	ds_write_b32 v215, v144 offset:768
.LBB0_1059:
	s_or_b64 exec, exec, s[12:13]
	v_add_co_u32_e32 v162, vcc, 0x80000, v180
	s_mov_b64 s[12:13], 0x80000
	s_nop 0
	v_addc_co_u32_e32 v163, vcc, 0, v181, vcc
	s_waitcnt lgkmcnt(0)
	global_load_dwordx4 v[144:147], v[162:163], off
	v_lshl_add_u64 v[148:149], v[180:181], 0, s[12:13]
	s_mov_b64 s[12:13], 0x80200
	global_load_dwordx4 v[148:151], v[148:149], off offset:16
	s_nop 0
	global_load_dwordx4 v[162:165], v[162:163], off offset:512
	v_lshl_add_u64 v[200:201], v[180:181], 0, s[12:13]
	global_load_dwordx4 v[200:203], v[200:201], off offset:16
	s_mov_b32 s12, 0x80000
	s_waitcnt vmcnt(3)
	v_pk_fma_f32 v[62:63], v[62:63], v[142:143], v[146:147]
	v_pk_fma_f32 v[60:61], v[60:61], v[140:141], v[144:145]
	s_waitcnt vmcnt(2)
	v_pk_fma_f32 v[58:59], v[58:59], v[138:139], v[150:151]
	v_pk_fma_f32 v[56:57], v[56:57], v[136:137], v[148:149]
	s_waitcnt vmcnt(1)
	v_pk_fma_f32 v[54:55], v[54:55], v[134:135], v[164:165]
	v_pk_fma_f32 v[52:53], v[52:53], v[132:133], v[162:163]
	v_mul_f32_e32 v144, v61, v61
	v_mul_f32_e32 v145, v63, v63
	v_mul_f32_e32 v146, v57, v57
	v_mul_f32_e32 v147, v59, v59
	s_waitcnt vmcnt(0)
	v_pk_fma_f32 v[50:51], v[50:51], v[130:131], v[202:203]
	v_pk_fma_f32 v[48:49], v[48:49], v[128:129], v[200:201]
	v_mul_f32_e32 v148, v53, v53
	v_mul_f32_e32 v149, v55, v55
	v_fmac_f32_e32 v144, v60, v60
	v_fmac_f32_e32 v145, v62, v62
	v_fmac_f32_e32 v146, v56, v56
	v_fmac_f32_e32 v147, v58, v58
	v_mul_f32_e32 v150, v49, v49
	v_mul_f32_e32 v151, v51, v51
	v_fmac_f32_e32 v148, v52, v52
	v_fmac_f32_e32 v149, v54, v54
	v_add_f32_e32 v144, v144, v145
	v_add_f32_e32 v145, v146, v147
	v_fmac_f32_e32 v150, v48, v48
	v_fmac_f32_e32 v151, v50, v50
	v_add_f32_e32 v146, v148, v149
	v_add_f32_e32 v144, v144, v145
	v_add_f32_e32 v147, v150, v151
	v_add_f32_e32 v144, v144, v146
	v_add_f32_e32 v144, v144, v147
	ds_bpermute_b32 v145, v213, v144
	v_add_co_u32_e32 v222, vcc, s12, v178
	s_waitcnt lgkmcnt(0)
	v_add_f32_e32 v144, v144, v145
	ds_bpermute_b32 v145, v214, v144
	v_addc_co_u32_e32 v223, vcc, 0, v179, vcc
	s_and_saveexec_b64 s[12:13], s[4:5]
	s_cbranch_execz .LBB0_1061
	s_waitcnt lgkmcnt(0)
	v_add_f32_e32 v144, v144, v145
	ds_write_b32 v187, v144
; #define LAS __attribute__((address_space(3)))
; #define EF_LOAD(buf, g_) do { const float* xp_ = xi + (size_t)(((g_) >> 2) * 128 + ((g_) & 3) * 16) * DM; \
;             _Pragma("unroll") for (int bj = 0; bj < 2; ++bj) _Pragma("unroll") for (int n = 0; n < 2; ++n) xv[buf][bj][n] = *(const f32x4*)(xp_ + bj * 128 + n * 4); } while (0)
;     __device__ __forceinline__ void fused(Acc& acc, const pg8::Unit& u, int wr, int wc, int fr, int fq, LAS unsigned char* lds, int wid, int lane) const {
;     ...
;         LAS float* P = (LAS float*)lds;
;         LAS float* S = (LAS float*)(lds + 4096);
; #pragma unroll
;         for (int g_ = 0; g_ < 8; ++g_) {
;             EF_LOAD(0, g_);
;             float sq = 0.f;
; #pragma unroll
;             for (int bj = 0; bj < 2; ++bj)
; #pragma unroll
;                 for (int n = 0; n < 2; ++n) { const f32x4 xn = xv[0][bj][n] + gt[bj][n] * acc[g_ >> 2][bj][g_ & 3][n]; acc[g_ >> 2][bj][g_ & 3][n] = xn;
;                     if (MODE == 1) *(f32x4*)(xo + (size_t)((g_ >> 2) * 128 + (g_ & 3) * 16) * DM + bj * 128 + n * 4) = xn;
;                     sq += (xn[0] * xn[0] + xn[1] * xn[1]) + (xn[2] * xn[2] + xn[3] * xn[3]); }
;             sq += __shfl_xor(sq, 16); sq += __shfl_xor(sq, 32);
;             if (fq == 0) P[((g_ >> 2) * 128 + wr * 64 + (g_ & 3) * 16 + fr) * 4 + wc] = sq;
.LBB0_1061:
	s_or_b64 exec, exec, s[12:13]
	v_add_co_u32_e32 v162, vcc, 0x90000, v180
	s_mov_b64 s[12:13], 0x90000
	s_nop 0
	v_addc_co_u32_e32 v163, vcc, 0, v181, vcc
	s_waitcnt lgkmcnt(0)
	global_load_dwordx4 v[144:147], v[162:163], off
	v_lshl_add_u64 v[148:149], v[180:181], 0, s[12:13]
	s_mov_b64 s[12:13], 0x90200
	global_load_dwordx4 v[148:151], v[148:149], off offset:16
	s_nop 0
	global_load_dwordx4 v[162:165], v[162:163], off offset:512
	v_lshl_add_u64 v[200:201], v[180:181], 0, s[12:13]
	global_load_dwordx4 v[200:203], v[200:201], off offset:16
	s_mov_b32 s12, 0x90000
	s_waitcnt vmcnt(3)
	v_pk_fma_f32 v[46:47], v[46:47], v[142:143], v[146:147]
	v_pk_fma_f32 v[44:45], v[44:45], v[140:141], v[144:145]
	s_waitcnt vmcnt(2)
	v_pk_fma_f32 v[42:43], v[42:43], v[138:139], v[150:151]
	v_pk_fma_f32 v[40:41], v[40:41], v[136:137], v[148:149]
	s_waitcnt vmcnt(1)
	v_pk_fma_f32 v[38:39], v[38:39], v[134:135], v[164:165]
	v_pk_fma_f32 v[36:37], v[36:37], v[132:133], v[162:163]
	v_mul_f32_e32 v144, v45, v45
	v_mul_f32_e32 v145, v47, v47
	v_mul_f32_e32 v146, v41, v41
	v_mul_f32_e32 v147, v43, v43
	s_waitcnt vmcnt(0)
	v_pk_fma_f32 v[34:35], v[34:35], v[130:131], v[202:203]
	v_pk_fma_f32 v[32:33], v[32:33], v[128:129], v[200:201]
	v_mul_f32_e32 v148, v37, v37
	v_mul_f32_e32 v149, v39, v39
	v_fmac_f32_e32 v144, v44, v44
	v_fmac_f32_e32 v145, v46, v46
	v_fmac_f32_e32 v146, v40, v40
	v_fmac_f32_e32 v147, v42, v42
	v_mul_f32_e32 v150, v33, v33
	v_mul_f32_e32 v151, v35, v35
	v_fmac_f32_e32 v148, v36, v36
	v_fmac_f32_e32 v149, v38, v38
	v_add_f32_e32 v144, v144, v145
	v_add_f32_e32 v145, v146, v147
	v_fmac_f32_e32 v150, v32, v32
	v_fmac_f32_e32 v151, v34, v34
	v_add_f32_e32 v146, v148, v149
	v_add_f32_e32 v144, v144, v145
	v_add_f32_e32 v147, v150, v151
	v_add_f32_e32 v144, v144, v146
	v_add_f32_e32 v144, v144, v147
	ds_bpermute_b32 v145, v213, v144
	v_add_co_u32_e32 v224, vcc, s12, v178
	s_waitcnt lgkmcnt(0)
	v_add_f32_e32 v144, v144, v145
	ds_bpermute_b32 v145, v214, v144
	v_addc_co_u32_e32 v225, vcc, 0, v179, vcc
	s_and_saveexec_b64 s[12:13], s[4:5]
	s_cbranch_execz .LBB0_1063
	s_waitcnt lgkmcnt(0)
	v_add_f32_e32 v144, v144, v145
	ds_write_b32 v188, v144
.LBB0_1063:
	s_or_b64 exec, exec, s[12:13]
	v_add_co_u32_e32 v162, vcc, 0xa0000, v180
	s_mov_b64 s[12:13], 0xa0000
	s_nop 0
	v_addc_co_u32_e32 v163, vcc, 0, v181, vcc
	v_lshl_add_u64 v[148:149], v[180:181], 0, s[12:13]
	s_mov_b64 s[12:13], 0xa0200
	s_waitcnt lgkmcnt(0)
	global_load_dwordx4 v[144:147], v[162:163], off
	v_lshl_add_u64 v[200:201], v[180:181], 0, s[12:13]
	global_load_dwordx4 v[148:151], v[148:149], off offset:16
	s_nop 0
	global_load_dwordx4 v[162:165], v[162:163], off offset:512
	s_mov_b32 s12, 0xa0000
	global_load_dwordx4 v[200:203], v[200:201], off offset:16
	s_waitcnt vmcnt(3)
	v_pk_fma_f32 v[146:147], v[30:31], v[142:143], v[146:147]
	v_pk_fma_f32 v[144:145], v[28:29], v[140:141], v[144:145]
	s_waitcnt vmcnt(2)
	v_pk_fma_f32 v[150:151], v[26:27], v[138:139], v[150:151]
	v_pk_fma_f32 v[148:149], v[24:25], v[136:137], v[148:149]
	s_waitcnt vmcnt(1)
	v_pk_fma_f32 v[26:27], v[22:23], v[134:135], v[164:165]
	v_pk_fma_f32 v[24:25], v[20:21], v[132:133], v[162:163]
	s_waitcnt vmcnt(0)
	v_pk_fma_f32 v[30:31], v[18:19], v[130:131], v[202:203]
	v_pk_fma_f32 v[28:29], v[16:17], v[128:129], v[200:201]
	v_mul_f32_e32 v16, v145, v145
	v_mul_f32_e32 v17, v147, v147
	v_mul_f32_e32 v18, v149, v149
	v_mul_f32_e32 v19, v151, v151
	v_mul_f32_e32 v20, v25, v25
	v_mul_f32_e32 v21, v27, v27
	v_fmac_f32_e32 v16, v144, v144
	v_fmac_f32_e32 v17, v146, v146
	v_fmac_f32_e32 v18, v148, v148
	v_fmac_f32_e32 v19, v150, v150
	v_mul_f32_e32 v22, v29, v29
	v_mul_f32_e32 v23, v31, v31
	v_fmac_f32_e32 v20, v24, v24
	v_fmac_f32_e32 v21, v26, v26
	v_add_f32_e32 v16, v16, v17
	v_add_f32_e32 v17, v18, v19
	v_fmac_f32_e32 v22, v28, v28
	v_fmac_f32_e32 v23, v30, v30
	v_add_f32_e32 v18, v20, v21
	v_add_f32_e32 v16, v16, v17
	v_add_f32_e32 v19, v22, v23
	v_add_f32_e32 v16, v16, v18
	v_add_f32_e32 v16, v16, v19
	ds_bpermute_b32 v17, v213, v16
	v_add_co_u32_e32 v226, vcc, s12, v178
	s_waitcnt lgkmcnt(0)
	v_add_f32_e32 v16, v16, v17
	ds_bpermute_b32 v17, v214, v16
	v_addc_co_u32_e32 v227, vcc, 0, v179, vcc
	s_and_saveexec_b64 s[12:13], s[4:5]
	s_cbranch_execz .LBB0_1065
	s_waitcnt lgkmcnt(0)
	v_add_f32_e32 v16, v16, v17
	ds_write_b32 v189, v16
; #define LAS __attribute__((address_space(3)))
; #define EF_LOAD(buf, g_) do { const float* xp_ = xi + (size_t)(((g_) >> 2) * 128 + ((g_) & 3) * 16) * DM; \
;             _Pragma("unroll") for (int bj = 0; bj < 2; ++bj) _Pragma("unroll") for (int n = 0; n < 2; ++n) xv[buf][bj][n] = *(const f32x4*)(xp_ + bj * 128 + n * 4); } while (0)
;     __device__ __forceinline__ void fused(Acc& acc, const pg8::Unit& u, int wr, int wc, int fr, int fq, LAS unsigned char* lds, int wid, int lane) const {
;     ...
;         LAS float* P = (LAS float*)lds;
;         LAS float* S = (LAS float*)(lds + 4096);
; #pragma unroll
;         for (int g_ = 0; g_ < 8; ++g_) {
;             EF_LOAD(0, g_);
;             float sq = 0.f;
; #pragma unroll
;             for (int bj = 0; bj < 2; ++bj)
; #pragma unroll
;                 for (int n = 0; n < 2; ++n) { const f32x4 xn = xv[0][bj][n] + gt[bj][n] * acc[g_ >> 2][bj][g_ & 3][n]; acc[g_ >> 2][bj][g_ & 3][n] = xn;
;                     if (MODE == 1) *(f32x4*)(xo + (size_t)((g_ >> 2) * 128 + (g_ & 3) * 16) * DM + bj * 128 + n * 4) = xn;
;                     sq += (xn[0] * xn[0] + xn[1] * xn[1]) + (xn[2] * xn[2] + xn[3] * xn[3]); }
;             sq += __shfl_xor(sq, 16); sq += __shfl_xor(sq, 32);
;             if (fq == 0) P[((g_ >> 2) * 128 + wr * 64 + (g_ & 3) * 16 + fr) * 4 + wc] = sq;
.LBB0_1065:
	s_or_b64 exec, exec, s[12:13]
	v_add_co_u32_e32 v162, vcc, 0xb0000, v180
	s_mov_b64 s[12:13], 0xb0000
	s_nop 0
	v_addc_co_u32_e32 v163, vcc, 0, v181, vcc
	s_waitcnt lgkmcnt(0)
	global_load_dwordx4 v[16:19], v[162:163], off
	v_lshl_add_u64 v[20:21], v[180:181], 0, s[12:13]
	s_mov_b64 s[12:13], 0xb0200
	global_load_dwordx4 v[20:23], v[20:21], off offset:16
	s_nop 0
	global_load_dwordx4 v[162:165], v[162:163], off offset:512
	v_lshl_add_u64 v[180:181], v[180:181], 0, s[12:13]
	global_load_dwordx4 v[200:203], v[180:181], off offset:16
	s_mov_b32 s12, 0xb0000
	s_waitcnt vmcnt(3)
	v_pk_fma_f32 v[14:15], v[14:15], v[142:143], v[18:19]
	v_pk_fma_f32 v[12:13], v[12:13], v[140:141], v[16:17]
	s_waitcnt vmcnt(2)
	v_pk_fma_f32 v[10:11], v[10:11], v[138:139], v[22:23]
	v_pk_fma_f32 v[8:9], v[8:9], v[136:137], v[20:21]
	s_waitcnt vmcnt(1)
	v_pk_fma_f32 v[2:3], v[2:3], v[134:135], v[164:165]
	v_pk_fma_f32 v[0:1], v[0:1], v[132:133], v[162:163]
	v_mul_f32_e32 v16, v13, v13
	v_mul_f32_e32 v17, v15, v15
	v_mul_f32_e32 v18, v9, v9
	v_mul_f32_e32 v19, v11, v11
	s_waitcnt vmcnt(0)
	v_pk_fma_f32 v[6:7], v[6:7], v[130:131], v[202:203]
	v_pk_fma_f32 v[4:5], v[4:5], v[128:129], v[200:201]
	v_mul_f32_e32 v20, v1, v1
	v_mul_f32_e32 v21, v3, v3
	v_fmac_f32_e32 v16, v12, v12
	v_fmac_f32_e32 v17, v14, v14
	v_fmac_f32_e32 v18, v8, v8
	v_fmac_f32_e32 v19, v10, v10
	v_mul_f32_e32 v22, v5, v5
	v_mul_f32_e32 v23, v7, v7
	v_fmac_f32_e32 v20, v0, v0
	v_fmac_f32_e32 v21, v2, v2
	v_add_f32_e32 v16, v16, v17
	v_add_f32_e32 v17, v18, v19
	v_fmac_f32_e32 v22, v4, v4
	v_fmac_f32_e32 v23, v6, v6
	v_add_f32_e32 v18, v20, v21
	v_add_f32_e32 v16, v16, v17
	v_add_f32_e32 v19, v22, v23
	v_add_f32_e32 v16, v16, v18
	v_add_f32_e32 v16, v16, v19
	ds_bpermute_b32 v17, v213, v16
	v_add_co_u32_e32 v18, vcc, s12, v178
	s_waitcnt lgkmcnt(0)
	v_add_f32_e32 v16, v16, v17
	ds_bpermute_b32 v17, v214, v16
	v_addc_co_u32_e32 v19, vcc, 0, v179, vcc
	global_store_dwordx4 v[178:179], v[112:115], off
	global_store_dwordx4 v[178:179], v[116:119], off offset:16
	global_store_dwordx4 v[178:179], v[64:67], off offset:512
	global_store_dwordx4 v[178:179], v[68:71], off offset:528
	global_store_dwordx4 v[216:217], v[120:123], off
	global_store_dwordx4 v[216:217], v[124:127], off offset:16
	global_store_dwordx4 v[216:217], v[84:87], off offset:512
	global_store_dwordx4 v[216:217], v[92:95], off offset:528
	global_store_dwordx4 v[218:219], v[108:111], off
	global_store_dwordx4 v[218:219], v[104:107], off offset:16
	global_store_dwordx4 v[218:219], v[100:103], off offset:512
	global_store_dwordx4 v[218:219], v[96:99], off offset:528
	global_store_dwordx4 v[220:221], v[88:91], off
	global_store_dwordx4 v[220:221], v[80:83], off offset:16
	global_store_dwordx4 v[220:221], v[76:79], off offset:512
	global_store_dwordx4 v[220:221], v[72:75], off offset:528
	global_store_dwordx4 v[222:223], v[60:63], off
	global_store_dwordx4 v[222:223], v[56:59], off offset:16
	global_store_dwordx4 v[222:223], v[52:55], off offset:512
	global_store_dwordx4 v[222:223], v[48:51], off offset:528
	global_store_dwordx4 v[224:225], v[44:47], off
	global_store_dwordx4 v[224:225], v[40:43], off offset:16
	global_store_dwordx4 v[224:225], v[36:39], off offset:512
	global_store_dwordx4 v[224:225], v[32:35], off offset:528
	global_store_dwordx4 v[226:227], v[144:147], off
	global_store_dwordx4 v[226:227], v[148:151], off offset:16
	global_store_dwordx4 v[226:227], v[24:27], off offset:512
	global_store_dwordx4 v[226:227], v[28:31], off offset:528
	global_store_dwordx4 v[18:19], v[12:15], off
	global_store_dwordx4 v[18:19], v[8:11], off offset:16
	global_store_dwordx4 v[18:19], v[0:3], off offset:512
	global_store_dwordx4 v[18:19], v[4:7], off offset:528
	s_and_saveexec_b64 s[12:13], s[4:5]
	s_cbranch_execz .LBB0_1067
	s_waitcnt lgkmcnt(0)
	v_add_f32_e32 v16, v16, v17
	ds_write_b32 v190, v16

; #define LAS __attribute__((address_space(3)))
; #define EF_LOAD(buf, g_) do { const float* xp_ = xi + (size_t)(((g_) >> 2) * 128 + ((g_) & 3) * 16) * DM; \
;             _Pragma("unroll") for (int bj = 0; bj < 2; ++bj) _Pragma("unroll") for (int n = 0; n < 2; ++n) xv[buf][bj][n] = *(const f32x4*)(xp_ + bj * 128 + n * 4); } while (0)
;     __device__ __forceinline__ void fused(Acc& acc, const pg8::Unit& u, int wr, int wc, int fr, int fq, LAS unsigned char* lds, int wid, int lane) const {
;         const int tile0 = u.pm * 256, colb = u.pn * 256 + wc * 32 + 8 * fq, rloc = wr * 64 + fr;
;         const float* xi = xin + (size_t)(tile0 + rloc) * DM + colb;
;         float* xo = out + (size_t)(tile0 + rloc) * DM + colb;
;         const float* gp = mod + (tile0 >> 11) * 6144 + goff + colb;
;         f32x4 gt[2][2];
; #pragma unroll
;         for (int bj = 0; bj < 2; ++bj)
; #pragma unroll
;             for (int n = 0; n < 2; ++n) gt[bj][n] = *(const f32x4*)(gp + bj * 128 + n * 4);
;         f32x4 xv[1][2][2];
;     ...
;         LAS float* P = (LAS float*)lds;
;         LAS float* S = (LAS float*)(lds + 4096);
; #pragma unroll
;         for (int g_ = 0; g_ < 8; ++g_) {
;             EF_LOAD(0, g_);
;             float sq = 0.f;
; #pragma unroll
;             for (int bj = 0; bj < 2; ++bj)
; #pragma unroll
;                 for (int n = 0; n < 2; ++n) { const f32x4 xn = xv[0][bj][n] + gt[bj][n] * acc[g_ >> 2][bj][g_ & 3][n]; acc[g_ >> 2][bj][g_ & 3][n] = xn;
;                     if (MODE == 1) *(f32x4*)(xo + (size_t)((g_ >> 2) * 128 + (g_ & 3) * 16) * DM + bj * 128 + n * 4) = xn;
;                     sq += (xn[0] * xn[0] + xn[1] * xn[1]) + (xn[2] * xn[2] + xn[3] * xn[3]); }
;             sq += __shfl_xor(sq, 16); sq += __shfl_xor(sq, 32);
;             if (fq == 0) P[((g_ >> 2) * 128 + wr * 64 + (g_ & 3) * 16 + fr) * 4 + wc] = sq;
.LBB0_1413:
	s_lshr_b32 s12, s93, 3
	s_mulk_i32 s12, 0x1800
	s_ashr_i32 s13, s12, 31
	s_lshl_b64 s[90:91], s[12:13], 2
	v_add_u32_e32 v172, s34, v158
	s_add_u32 s12, s48, s90
	v_ashrrev_i32_e32 v173, 31, v172
	v_readlane_b32 s68, v252, 0
	s_addc_u32 s13, s49, s91
	v_lshlrev_b64 v[174:175], 2, v[170:171]
	v_lshlrev_b64 v[128:129], 12, v[172:173]
	v_readlane_b32 s70, v252, 2
	v_readlane_b32 s71, v252, 3
	v_lshl_add_u64 v[130:131], s[12:13], 0, v[174:175]
	s_movk_i32 s12, 0x5000
	v_lshl_add_u64 v[128:129], s[70:71], 0, v[128:129]
	v_add_co_u32_e32 v132, vcc, s12, v130
	v_lshl_add_u64 v[176:177], v[128:129], 0, v[174:175]
	s_nop 0
	v_addc_co_u32_e32 v133, vcc, 0, v131, vcc
	global_load_dwordx4 v[140:143], v[132:133], off
	global_load_dwordx4 v[144:147], v[176:177], off offset:16
	global_load_dwordx4 v[148:151], v[176:177], off
	s_mov_b64 s[12:13], 0x5000
	v_lshl_add_u64 v[128:129], v[130:131], 0, s[12:13]
	global_load_dwordx4 v[136:139], v[128:129], off offset:16
	global_load_dwordx4 v[132:135], v[128:129], off offset:512
	global_load_dwordx4 v[162:165], v[176:177], off offset:512
	global_load_dwordx4 v[200:203], v[176:177], off offset:528
	s_nop 0
	global_load_dwordx4 v[128:131], v[128:129], off offset:528
	v_readlane_b32 s69, v252, 1
	v_readlane_b32 s72, v252, 4
	v_readlane_b32 s73, v252, 5
	v_readlane_b32 s74, v252, 6
	v_readlane_b32 s75, v252, 7
	s_waitcnt vmcnt(0)
	v_pk_fma_f32 v[118:119], v[118:119], v[138:139], v[146:147]
	v_pk_fma_f32 v[114:115], v[114:115], v[142:143], v[150:151]
	v_pk_fma_f32 v[112:113], v[112:113], v[140:141], v[148:149]
	v_pk_fma_f32 v[116:117], v[116:117], v[136:137], v[144:145]
	v_pk_fma_f32 v[62:63], v[62:63], v[134:135], v[164:165]
	v_pk_fma_f32 v[60:61], v[60:61], v[132:133], v[162:163]
	v_mul_f32_e32 v144, v113, v113
	v_mul_f32_e32 v145, v115, v115
	v_mul_f32_e32 v146, v117, v117
	v_mul_f32_e32 v147, v119, v119
	v_pk_fma_f32 v[66:67], v[66:67], v[130:131], v[202:203]
	v_pk_fma_f32 v[64:65], v[64:65], v[128:129], v[200:201]
	v_mul_f32_e32 v148, v61, v61
	v_mul_f32_e32 v149, v63, v63
	v_fmac_f32_e32 v144, v112, v112
	v_fmac_f32_e32 v145, v114, v114
	v_fmac_f32_e32 v146, v116, v116
	v_fmac_f32_e32 v147, v118, v118
	v_mul_f32_e32 v150, v65, v65
	v_mul_f32_e32 v151, v67, v67
	v_fmac_f32_e32 v148, v60, v60
	v_fmac_f32_e32 v149, v62, v62
	v_add_f32_e32 v144, v144, v145
	v_add_f32_e32 v145, v146, v147
	v_fmac_f32_e32 v150, v64, v64
	v_fmac_f32_e32 v151, v66, v66
	v_add_f32_e32 v146, v148, v149
	v_add_f32_e32 v144, v144, v145
	v_add_f32_e32 v144, v144, v146
	v_add_f32_e32 v145, v150, v151
	v_add_f32_e32 v144, v144, v145
	ds_bpermute_b32 v145, v213, v144
	v_mov_b32_e32 v230, v176
	v_mov_b32_e32 v231, v177
	s_waitcnt lgkmcnt(0)
	v_add_f32_e32 v144, v144, v145
	ds_bpermute_b32 v145, v214, v144
	s_and_saveexec_b64 s[12:13], s[0:1]
	s_cbranch_execz .LBB0_1415
	s_waitcnt lgkmcnt(0)
	v_add_f32_e32 v144, v144, v145
	ds_write_b32 v188, v144
.LBB0_1415:
	s_or_b64 exec, exec, s[12:13]
	v_add_co_u32_e32 v190, vcc, 0x10000, v176
	v_lshl_add_u64 v[148:149], v[176:177], 0, s[88:89]
	s_nop 0
	v_addc_co_u32_e32 v191, vcc, 0, v177, vcc
	v_mov_b32_e32 v216, v190
	v_mov_b32_e32 v217, v191
	s_waitcnt lgkmcnt(0)
	global_load_dwordx4 v[144:147], v[190:191], off
	s_mov_b64 s[12:13], 0x10200
	global_load_dwordx4 v[148:151], v[148:149], off offset:16
	s_nop 0
	global_load_dwordx4 v[162:165], v[190:191], off offset:512
	v_lshl_add_u64 v[200:201], v[176:177], 0, s[12:13]
	global_load_dwordx4 v[200:203], v[200:201], off offset:16
	s_waitcnt vmcnt(3)
	v_pk_fma_f32 v[122:123], v[122:123], v[142:143], v[146:147]
	v_pk_fma_f32 v[120:121], v[120:121], v[140:141], v[144:145]
	s_waitcnt vmcnt(2)
	v_pk_fma_f32 v[126:127], v[126:127], v[138:139], v[150:151]
	v_pk_fma_f32 v[124:125], v[124:125], v[136:137], v[148:149]
	s_waitcnt vmcnt(1)
	v_pk_fma_f32 v[78:79], v[78:79], v[134:135], v[164:165]
	v_pk_fma_f32 v[76:77], v[76:77], v[132:133], v[162:163]
	v_mul_f32_e32 v144, v121, v121
	v_mul_f32_e32 v145, v123, v123
	v_mul_f32_e32 v146, v125, v125
	v_mul_f32_e32 v147, v127, v127
	s_waitcnt vmcnt(0)
	v_pk_fma_f32 v[90:91], v[90:91], v[130:131], v[202:203]
	v_pk_fma_f32 v[88:89], v[88:89], v[128:129], v[200:201]
	v_mul_f32_e32 v148, v77, v77
	v_mul_f32_e32 v149, v79, v79
	v_fmac_f32_e32 v144, v120, v120
	v_fmac_f32_e32 v145, v122, v122
	v_fmac_f32_e32 v146, v124, v124
	v_fmac_f32_e32 v147, v126, v126
	v_mul_f32_e32 v150, v89, v89
	v_mul_f32_e32 v151, v91, v91
	v_fmac_f32_e32 v148, v76, v76
	v_fmac_f32_e32 v149, v78, v78
	v_add_f32_e32 v144, v144, v145
	v_add_f32_e32 v145, v146, v147
	v_fmac_f32_e32 v150, v88, v88
	v_fmac_f32_e32 v151, v90, v90
	v_add_f32_e32 v146, v148, v149
	v_add_f32_e32 v144, v144, v145
	v_add_f32_e32 v144, v144, v146
	v_add_f32_e32 v145, v150, v151
	v_add_f32_e32 v144, v144, v145
	ds_bpermute_b32 v145, v213, v144
	s_waitcnt lgkmcnt(0)
	v_add_f32_e32 v144, v144, v145
	ds_bpermute_b32 v145, v214, v144
	s_and_saveexec_b64 s[12:13], s[0:1]
	s_cbranch_execz .LBB0_1417
	s_waitcnt lgkmcnt(0)
	v_add_f32_e32 v144, v144, v145
	ds_write_b32 v188, v144 offset:256
; #define EF_LOAD(buf, g_) do { const float* xp_ = xi + (size_t)(((g_) >> 2) * 128 + ((g_) & 3) * 16) * DM; \
;             _Pragma("unroll") for (int bj = 0; bj < 2; ++bj) _Pragma("unroll") for (int n = 0; n < 2; ++n) xv[buf][bj][n] = *(const f32x4*)(xp_ + bj * 128 + n * 4); } while (0)
;     __device__ __forceinline__ void fused(Acc& acc, const pg8::Unit& u, int wr, int wc, int fr, int fq, LAS unsigned char* lds, int wid, int lane) const {
;     ...
;         for (int g_ = 0; g_ < 8; ++g_) {
;             EF_LOAD(0, g_);
;             float sq = 0.f;
; #pragma unroll
;             for (int bj = 0; bj < 2; ++bj)
; #pragma unroll
;                 for (int n = 0; n < 2; ++n) { const f32x4 xn = xv[0][bj][n] + gt[bj][n] * acc[g_ >> 2][bj][g_ & 3][n]; acc[g_ >> 2][bj][g_ & 3][n] = xn;
;                     if (MODE == 1) *(f32x4*)(xo + (size_t)((g_ >> 2) * 128 + (g_ & 3) * 16) * DM + bj * 128 + n * 4) = xn;
;                     sq += (xn[0] * xn[0] + xn[1] * xn[1]) + (xn[2] * xn[2] + xn[3] * xn[3]); }
;             sq += __shfl_xor(sq, 16); sq += __shfl_xor(sq, 32);
;             if (fq == 0) P[((g_ >> 2) * 128 + wr * 64 + (g_ & 3) * 16 + fr) * 4 + wc] = sq;
;         }
.LBB0_1417:
	s_or_b64 exec, exec, s[12:13]
	v_add_co_u32_e32 v190, vcc, 0x20000, v176
	s_mov_b64 s[12:13], 0x20000
	s_nop 0
	v_addc_co_u32_e32 v191, vcc, 0, v177, vcc
	v_mov_b32_e32 v218, v190
	v_mov_b32_e32 v219, v191
	s_waitcnt lgkmcnt(0)
	global_load_dwordx4 v[144:147], v[190:191], off
	v_lshl_add_u64 v[148:149], v[176:177], 0, s[12:13]
	s_mov_b64 s[12:13], 0x20200
	global_load_dwordx4 v[148:151], v[148:149], off offset:16
	s_nop 0
	global_load_dwordx4 v[162:165], v[190:191], off offset:512
	v_lshl_add_u64 v[200:201], v[176:177], 0, s[12:13]
	global_load_dwordx4 v[200:203], v[200:201], off offset:16
	s_waitcnt vmcnt(3)
	v_pk_fma_f32 v[110:111], v[110:111], v[142:143], v[146:147]
	v_pk_fma_f32 v[108:109], v[108:109], v[140:141], v[144:145]
	s_waitcnt vmcnt(2)
	v_pk_fma_f32 v[106:107], v[106:107], v[138:139], v[150:151]
	v_pk_fma_f32 v[104:105], v[104:105], v[136:137], v[148:149]
	s_waitcnt vmcnt(1)
	v_pk_fma_f32 v[102:103], v[102:103], v[134:135], v[164:165]
	v_pk_fma_f32 v[100:101], v[100:101], v[132:133], v[162:163]
	v_mul_f32_e32 v144, v109, v109
	v_mul_f32_e32 v145, v111, v111
	v_mul_f32_e32 v146, v105, v105
	v_mul_f32_e32 v147, v107, v107
	s_waitcnt vmcnt(0)
	v_pk_fma_f32 v[98:99], v[98:99], v[130:131], v[202:203]
	v_pk_fma_f32 v[96:97], v[96:97], v[128:129], v[200:201]
	v_mul_f32_e32 v148, v101, v101
	v_mul_f32_e32 v149, v103, v103
	v_fmac_f32_e32 v144, v108, v108
	v_fmac_f32_e32 v145, v110, v110
	v_fmac_f32_e32 v146, v104, v104
	v_fmac_f32_e32 v147, v106, v106
	v_mul_f32_e32 v150, v97, v97
	v_mul_f32_e32 v151, v99, v99
	v_fmac_f32_e32 v148, v100, v100
	v_fmac_f32_e32 v149, v102, v102
	v_add_f32_e32 v144, v144, v145
	v_add_f32_e32 v145, v146, v147
	v_fmac_f32_e32 v150, v96, v96
	v_fmac_f32_e32 v151, v98, v98
	v_add_f32_e32 v146, v148, v149
	v_add_f32_e32 v144, v144, v145
	v_add_f32_e32 v144, v144, v146
	v_add_f32_e32 v145, v150, v151
	v_add_f32_e32 v144, v144, v145
	ds_bpermute_b32 v145, v213, v144
	s_waitcnt lgkmcnt(0)
	v_add_f32_e32 v144, v144, v145
	ds_bpermute_b32 v145, v214, v144
	s_and_saveexec_b64 s[12:13], s[0:1]
	s_cbranch_execz .LBB0_1419
	s_waitcnt lgkmcnt(0)
	v_add_f32_e32 v144, v144, v145
	ds_write_b32 v188, v144 offset:512
.LBB0_1419:
	s_or_b64 exec, exec, s[12:13]
	v_add_co_u32_e32 v190, vcc, 0x30000, v176
	s_mov_b64 s[12:13], 0x30000
	s_nop 0
	v_addc_co_u32_e32 v191, vcc, 0, v177, vcc
	v_mov_b32_e32 v220, v190
	v_mov_b32_e32 v221, v191
	s_waitcnt lgkmcnt(0)
	global_load_dwordx4 v[144:147], v[190:191], off
	v_lshl_add_u64 v[148:149], v[176:177], 0, s[12:13]
	s_mov_b64 s[12:13], 0x30200
	global_load_dwordx4 v[148:151], v[148:149], off offset:16
	s_nop 0
	global_load_dwordx4 v[162:165], v[190:191], off offset:512
	v_lshl_add_u64 v[200:201], v[176:177], 0, s[12:13]
	global_load_dwordx4 v[200:203], v[200:201], off offset:16
	s_waitcnt vmcnt(3)
	v_pk_fma_f32 v[94:95], v[94:95], v[142:143], v[146:147]
	v_pk_fma_f32 v[92:93], v[92:93], v[140:141], v[144:145]
	s_waitcnt vmcnt(2)
	v_pk_fma_f32 v[86:87], v[86:87], v[138:139], v[150:151]
	v_pk_fma_f32 v[84:85], v[84:85], v[136:137], v[148:149]
	s_waitcnt vmcnt(1)
	v_pk_fma_f32 v[82:83], v[82:83], v[134:135], v[164:165]
	v_pk_fma_f32 v[80:81], v[80:81], v[132:133], v[162:163]
	v_mul_f32_e32 v144, v93, v93
	v_mul_f32_e32 v145, v95, v95
	v_mul_f32_e32 v146, v85, v85
	v_mul_f32_e32 v147, v87, v87
	s_waitcnt vmcnt(0)
	v_pk_fma_f32 v[74:75], v[74:75], v[130:131], v[202:203]
	v_pk_fma_f32 v[72:73], v[72:73], v[128:129], v[200:201]
	v_mul_f32_e32 v148, v81, v81
	v_mul_f32_e32 v149, v83, v83
	v_fmac_f32_e32 v144, v92, v92
	v_fmac_f32_e32 v145, v94, v94
	v_fmac_f32_e32 v146, v84, v84
	v_fmac_f32_e32 v147, v86, v86
	v_mul_f32_e32 v150, v73, v73
	v_mul_f32_e32 v151, v75, v75
	v_fmac_f32_e32 v148, v80, v80
	v_fmac_f32_e32 v149, v82, v82
	v_add_f32_e32 v144, v144, v145
	v_add_f32_e32 v145, v146, v147
	v_fmac_f32_e32 v150, v72, v72
	v_fmac_f32_e32 v151, v74, v74
	v_add_f32_e32 v146, v148, v149
	v_add_f32_e32 v144, v144, v145
	v_add_f32_e32 v144, v144, v146
	v_add_f32_e32 v145, v150, v151
	v_add_f32_e32 v144, v144, v145
	ds_bpermute_b32 v145, v213, v144
	s_waitcnt lgkmcnt(0)
	v_add_f32_e32 v144, v144, v145
	ds_bpermute_b32 v145, v214, v144
	s_and_saveexec_b64 s[12:13], s[0:1]
	s_cbranch_execz .LBB0_1421
	s_waitcnt lgkmcnt(0)
	v_add_f32_e32 v144, v144, v145
	ds_write_b32 v188, v144 offset:768
.LBB0_1421:
	s_or_b64 exec, exec, s[12:13]
	v_add_co_u32_e32 v190, vcc, 0x80000, v176
	s_mov_b64 s[12:13], 0x80000
	s_nop 0
	v_addc_co_u32_e32 v191, vcc, 0, v177, vcc
	v_mov_b32_e32 v222, v190
	v_mov_b32_e32 v223, v191
	s_waitcnt lgkmcnt(0)
	global_load_dwordx4 v[144:147], v[190:191], off
	v_lshl_add_u64 v[148:149], v[176:177], 0, s[12:13]
	s_mov_b64 s[12:13], 0x80200
	global_load_dwordx4 v[148:151], v[148:149], off offset:16
	s_nop 0
	global_load_dwordx4 v[162:165], v[190:191], off offset:512
	v_lshl_add_u64 v[200:201], v[176:177], 0, s[12:13]
	global_load_dwordx4 v[200:203], v[200:201], off offset:16
	s_waitcnt vmcnt(3)
	v_pk_fma_f32 v[70:71], v[70:71], v[142:143], v[146:147]
	v_pk_fma_f32 v[68:69], v[68:69], v[140:141], v[144:145]
	s_waitcnt vmcnt(2)
	v_pk_fma_f32 v[58:59], v[58:59], v[138:139], v[150:151]
	v_pk_fma_f32 v[56:57], v[56:57], v[136:137], v[148:149]
	s_waitcnt vmcnt(1)
	v_pk_fma_f32 v[54:55], v[54:55], v[134:135], v[164:165]
	v_pk_fma_f32 v[52:53], v[52:53], v[132:133], v[162:163]
	v_mul_f32_e32 v144, v69, v69
	v_mul_f32_e32 v145, v71, v71
	v_mul_f32_e32 v146, v57, v57
	v_mul_f32_e32 v147, v59, v59
	s_waitcnt vmcnt(0)
	v_pk_fma_f32 v[50:51], v[50:51], v[130:131], v[202:203]
	v_pk_fma_f32 v[48:49], v[48:49], v[128:129], v[200:201]
	v_mul_f32_e32 v148, v53, v53
	v_mul_f32_e32 v149, v55, v55
	v_fmac_f32_e32 v144, v68, v68
	v_fmac_f32_e32 v145, v70, v70
	v_fmac_f32_e32 v146, v56, v56
	v_fmac_f32_e32 v147, v58, v58
	v_mul_f32_e32 v150, v49, v49
	v_mul_f32_e32 v151, v51, v51
	v_fmac_f32_e32 v148, v52, v52
	v_fmac_f32_e32 v149, v54, v54
	v_add_f32_e32 v144, v144, v145
	v_add_f32_e32 v145, v146, v147
	v_fmac_f32_e32 v150, v48, v48
	v_fmac_f32_e32 v151, v50, v50
	v_add_f32_e32 v146, v148, v149
	v_add_f32_e32 v144, v144, v145
	v_add_f32_e32 v144, v144, v146
	v_add_f32_e32 v145, v150, v151
	v_add_f32_e32 v144, v144, v145
	ds_bpermute_b32 v145, v213, v144
	s_waitcnt lgkmcnt(0)
	v_add_f32_e32 v144, v144, v145
	ds_bpermute_b32 v145, v214, v144
	s_and_saveexec_b64 s[12:13], s[0:1]
	s_cbranch_execz .LBB0_1423
	s_waitcnt lgkmcnt(0)
	v_add_f32_e32 v144, v144, v145
	ds_write_b32 v183, v144
; #define EF_LOAD(buf, g_) do { const float* xp_ = xi + (size_t)(((g_) >> 2) * 128 + ((g_) & 3) * 16) * DM; \
;             _Pragma("unroll") for (int bj = 0; bj < 2; ++bj) _Pragma("unroll") for (int n = 0; n < 2; ++n) xv[buf][bj][n] = *(const f32x4*)(xp_ + bj * 128 + n * 4); } while (0)
;     __device__ __forceinline__ void fused(Acc& acc, const pg8::Unit& u, int wr, int wc, int fr, int fq, LAS unsigned char* lds, int wid, int lane) const {
;     ...
;         for (int g_ = 0; g_ < 8; ++g_) {
;             EF_LOAD(0, g_);
;             float sq = 0.f;
; #pragma unroll
;             for (int bj = 0; bj < 2; ++bj)
; #pragma unroll
;                 for (int n = 0; n < 2; ++n) { const f32x4 xn = xv[0][bj][n] + gt[bj][n] * acc[g_ >> 2][bj][g_ & 3][n]; acc[g_ >> 2][bj][g_ & 3][n] = xn;
;                     if (MODE == 1) *(f32x4*)(xo + (size_t)((g_ >> 2) * 128 + (g_ & 3) * 16) * DM + bj * 128 + n * 4) = xn;
;                     sq += (xn[0] * xn[0] + xn[1] * xn[1]) + (xn[2] * xn[2] + xn[3] * xn[3]); }
;             sq += __shfl_xor(sq, 16); sq += __shfl_xor(sq, 32);
;             if (fq == 0) P[((g_ >> 2) * 128 + wr * 64 + (g_ & 3) * 16 + fr) * 4 + wc] = sq;
;         }
.LBB0_1423:
	s_or_b64 exec, exec, s[12:13]
	v_add_co_u32_e32 v190, vcc, 0x90000, v176
	s_mov_b64 s[12:13], 0x90000
	s_nop 0
	v_addc_co_u32_e32 v191, vcc, 0, v177, vcc
	v_mov_b32_e32 v224, v190
	v_mov_b32_e32 v225, v191
	s_waitcnt lgkmcnt(0)
	global_load_dwordx4 v[144:147], v[190:191], off
	v_lshl_add_u64 v[148:149], v[176:177], 0, s[12:13]
	s_mov_b64 s[12:13], 0x90200
	global_load_dwordx4 v[148:151], v[148:149], off offset:16
	s_nop 0
	global_load_dwordx4 v[162:165], v[190:191], off offset:512
	v_lshl_add_u64 v[200:201], v[176:177], 0, s[12:13]
	global_load_dwordx4 v[200:203], v[200:201], off offset:16
	s_waitcnt vmcnt(3)
	v_pk_fma_f32 v[46:47], v[46:47], v[142:143], v[146:147]
	v_pk_fma_f32 v[44:45], v[44:45], v[140:141], v[144:145]
	s_waitcnt vmcnt(2)
	v_pk_fma_f32 v[42:43], v[42:43], v[138:139], v[150:151]
	v_pk_fma_f32 v[40:41], v[40:41], v[136:137], v[148:149]
	s_waitcnt vmcnt(1)
	v_pk_fma_f32 v[38:39], v[38:39], v[134:135], v[164:165]
	v_pk_fma_f32 v[36:37], v[36:37], v[132:133], v[162:163]
	v_mul_f32_e32 v144, v45, v45
	v_mul_f32_e32 v145, v47, v47
	v_mul_f32_e32 v146, v41, v41
	v_mul_f32_e32 v147, v43, v43
	s_waitcnt vmcnt(0)
	v_pk_fma_f32 v[34:35], v[34:35], v[130:131], v[202:203]
	v_pk_fma_f32 v[32:33], v[32:33], v[128:129], v[200:201]
	v_mul_f32_e32 v148, v37, v37
	v_mul_f32_e32 v149, v39, v39
	v_fmac_f32_e32 v144, v44, v44
	v_fmac_f32_e32 v145, v46, v46
	v_fmac_f32_e32 v146, v40, v40
	v_fmac_f32_e32 v147, v42, v42
	v_mul_f32_e32 v150, v33, v33
	v_mul_f32_e32 v151, v35, v35
	v_fmac_f32_e32 v148, v36, v36
	v_fmac_f32_e32 v149, v38, v38
	v_add_f32_e32 v144, v144, v145
	v_add_f32_e32 v145, v146, v147
	v_fmac_f32_e32 v150, v32, v32
	v_fmac_f32_e32 v151, v34, v34
	v_add_f32_e32 v146, v148, v149
	v_add_f32_e32 v144, v144, v145
	v_add_f32_e32 v144, v144, v146
	v_add_f32_e32 v145, v150, v151
	v_add_f32_e32 v144, v144, v145
	ds_bpermute_b32 v145, v213, v144
	s_waitcnt lgkmcnt(0)
	v_add_f32_e32 v144, v144, v145
	ds_bpermute_b32 v145, v214, v144
	s_and_saveexec_b64 s[12:13], s[0:1]
	s_cbranch_execz .LBB0_1425
	s_waitcnt lgkmcnt(0)
	v_add_f32_e32 v144, v144, v145
	ds_write_b32 v184, v144
.LBB0_1425:
	s_or_b64 exec, exec, s[12:13]
	v_add_co_u32_e32 v190, vcc, 0xa0000, v176
	s_mov_b64 s[12:13], 0xa0000
	s_nop 0
	v_addc_co_u32_e32 v191, vcc, 0, v177, vcc
	v_mov_b32_e32 v226, v190
	v_mov_b32_e32 v227, v191
	v_lshl_add_u64 v[148:149], v[176:177], 0, s[12:13]
	s_mov_b64 s[12:13], 0xa0200
	s_waitcnt lgkmcnt(0)
	global_load_dwordx4 v[144:147], v[190:191], off
	v_lshl_add_u64 v[200:201], v[176:177], 0, s[12:13]
	global_load_dwordx4 v[148:151], v[148:149], off offset:16
	s_nop 0
	global_load_dwordx4 v[162:165], v[190:191], off offset:512
	s_waitcnt vmcnt(2)
	v_pk_fma_f32 v[146:147], v[30:31], v[142:143], v[146:147]
	global_load_dwordx4 v[200:203], v[200:201], off offset:16
	v_pk_fma_f32 v[144:145], v[28:29], v[140:141], v[144:145]
	s_waitcnt vmcnt(2)
	v_pk_fma_f32 v[150:151], v[26:27], v[138:139], v[150:151]
	v_pk_fma_f32 v[148:149], v[24:25], v[136:137], v[148:149]
	s_waitcnt vmcnt(1)
	v_pk_fma_f32 v[26:27], v[22:23], v[134:135], v[164:165]
	v_pk_fma_f32 v[24:25], v[20:21], v[132:133], v[162:163]
	v_mul_f32_e32 v21, v27, v27
	v_mul_f32_e32 v20, v25, v25
	v_fmac_f32_e32 v20, v24, v24
	v_fmac_f32_e32 v21, v26, v26
	s_waitcnt vmcnt(0)
	v_pk_fma_f32 v[30:31], v[18:19], v[130:131], v[202:203]
	v_pk_fma_f32 v[28:29], v[16:17], v[128:129], v[200:201]
	v_mul_f32_e32 v16, v145, v145
	v_mul_f32_e32 v17, v147, v147
	v_mul_f32_e32 v18, v149, v149
	v_mul_f32_e32 v19, v151, v151
	v_fmac_f32_e32 v16, v144, v144
	v_fmac_f32_e32 v17, v146, v146
	v_fmac_f32_e32 v18, v148, v148
	v_fmac_f32_e32 v19, v150, v150
	v_mul_f32_e32 v22, v29, v29
	v_mul_f32_e32 v23, v31, v31
	v_add_f32_e32 v16, v16, v17
	v_add_f32_e32 v17, v18, v19
	v_fmac_f32_e32 v22, v28, v28
	v_fmac_f32_e32 v23, v30, v30
	v_add_f32_e32 v18, v20, v21
	v_add_f32_e32 v16, v16, v17
	v_add_f32_e32 v16, v16, v18
	v_add_f32_e32 v17, v22, v23
	v_add_f32_e32 v16, v16, v17
	ds_bpermute_b32 v17, v213, v16
	s_waitcnt lgkmcnt(0)
	v_add_f32_e32 v16, v16, v17
	ds_bpermute_b32 v17, v214, v16
	s_and_saveexec_b64 s[12:13], s[0:1]
	s_cbranch_execz .LBB0_1427
	s_waitcnt lgkmcnt(0)
	v_add_f32_e32 v16, v16, v17
	ds_write_b32 v185, v16
; #define EF_LOAD(buf, g_) do { const float* xp_ = xi + (size_t)(((g_) >> 2) * 128 + ((g_) & 3) * 16) * DM; \
;             _Pragma("unroll") for (int bj = 0; bj < 2; ++bj) _Pragma("unroll") for (int n = 0; n < 2; ++n) xv[buf][bj][n] = *(const f32x4*)(xp_ + bj * 128 + n * 4); } while (0)
;     __device__ __forceinline__ void fused(Acc& acc, const pg8::Unit& u, int wr, int wc, int fr, int fq, LAS unsigned char* lds, int wid, int lane) const {
;     ...
;         for (int g_ = 0; g_ < 8; ++g_) {
;             EF_LOAD(0, g_);
;             float sq = 0.f;
; #pragma unroll
;             for (int bj = 0; bj < 2; ++bj)
; #pragma unroll
;                 for (int n = 0; n < 2; ++n) { const f32x4 xn = xv[0][bj][n] + gt[bj][n] * acc[g_ >> 2][bj][g_ & 3][n]; acc[g_ >> 2][bj][g_ & 3][n] = xn;
;                     if (MODE == 1) *(f32x4*)(xo + (size_t)((g_ >> 2) * 128 + (g_ & 3) * 16) * DM + bj * 128 + n * 4) = xn;
;                     sq += (xn[0] * xn[0] + xn[1] * xn[1]) + (xn[2] * xn[2] + xn[3] * xn[3]); }
;             sq += __shfl_xor(sq, 16); sq += __shfl_xor(sq, 32);
;             if (fq == 0) P[((g_ >> 2) * 128 + wr * 64 + (g_ & 3) * 16 + fr) * 4 + wc] = sq;
;         }
.LBB0_1427:
	s_or_b64 exec, exec, s[12:13]
	v_add_co_u32_e32 v190, vcc, 0xb0000, v176
	s_mov_b64 s[12:13], 0xb0000
	s_nop 0
	v_addc_co_u32_e32 v191, vcc, 0, v177, vcc
	s_waitcnt lgkmcnt(0)
	global_load_dwordx4 v[16:19], v[190:191], off
	v_lshl_add_u64 v[20:21], v[176:177], 0, s[12:13]
	s_mov_b64 s[12:13], 0xb0200
	global_load_dwordx4 v[20:23], v[20:21], off offset:16
	s_nop 0
	global_load_dwordx4 v[162:165], v[190:191], off offset:512
	v_lshl_add_u64 v[176:177], v[176:177], 0, s[12:13]
	global_load_dwordx4 v[200:203], v[176:177], off offset:16
	s_waitcnt vmcnt(3)
	v_pk_fma_f32 v[14:15], v[14:15], v[142:143], v[18:19]
	v_pk_fma_f32 v[12:13], v[12:13], v[140:141], v[16:17]
	s_waitcnt vmcnt(2)
	v_pk_fma_f32 v[10:11], v[10:11], v[138:139], v[22:23]
	v_pk_fma_f32 v[8:9], v[8:9], v[136:137], v[20:21]
	s_waitcnt vmcnt(1)
	v_pk_fma_f32 v[2:3], v[2:3], v[134:135], v[164:165]
	v_pk_fma_f32 v[0:1], v[0:1], v[132:133], v[162:163]
	v_mul_f32_e32 v16, v13, v13
	v_mul_f32_e32 v17, v15, v15
	v_mul_f32_e32 v18, v9, v9
	v_mul_f32_e32 v19, v11, v11
	s_waitcnt vmcnt(0)
	v_pk_fma_f32 v[6:7], v[6:7], v[130:131], v[202:203]
	v_pk_fma_f32 v[4:5], v[4:5], v[128:129], v[200:201]
	v_mul_f32_e32 v20, v1, v1
	v_mul_f32_e32 v21, v3, v3
	v_fmac_f32_e32 v16, v12, v12
	v_fmac_f32_e32 v17, v14, v14
	v_fmac_f32_e32 v18, v8, v8
	v_fmac_f32_e32 v19, v10, v10
	v_mul_f32_e32 v22, v5, v5
	v_mul_f32_e32 v23, v7, v7
	v_fmac_f32_e32 v20, v0, v0
	v_fmac_f32_e32 v21, v2, v2
	v_add_f32_e32 v16, v16, v17
	v_add_f32_e32 v17, v18, v19
	v_fmac_f32_e32 v22, v4, v4
	v_fmac_f32_e32 v23, v6, v6
	v_add_f32_e32 v18, v20, v21
	v_add_f32_e32 v16, v16, v17
	v_add_f32_e32 v16, v16, v18
	v_add_f32_e32 v17, v22, v23
	v_add_f32_e32 v16, v16, v17
	ds_bpermute_b32 v17, v213, v16
	global_store_dwordx4 v[230:231], v[112:115], off
	global_store_dwordx4 v[230:231], v[116:119], off offset:16
	global_store_dwordx4 v[230:231], v[60:63], off offset:512
	global_store_dwordx4 v[230:231], v[64:67], off offset:528
	global_store_dwordx4 v[216:217], v[120:123], off
	global_store_dwordx4 v[216:217], v[124:127], off offset:16
	global_store_dwordx4 v[216:217], v[76:79], off offset:512
	global_store_dwordx4 v[216:217], v[88:91], off offset:528
	global_store_dwordx4 v[218:219], v[108:111], off
	global_store_dwordx4 v[218:219], v[104:107], off offset:16
	global_store_dwordx4 v[218:219], v[100:103], off offset:512
	global_store_dwordx4 v[218:219], v[96:99], off offset:528
	global_store_dwordx4 v[220:221], v[92:95], off
	global_store_dwordx4 v[220:221], v[84:87], off offset:16
	global_store_dwordx4 v[220:221], v[80:83], off offset:512
	global_store_dwordx4 v[220:221], v[72:75], off offset:528
	global_store_dwordx4 v[222:223], v[68:71], off
	global_store_dwordx4 v[222:223], v[56:59], off offset:16
	global_store_dwordx4 v[222:223], v[52:55], off offset:512
	global_store_dwordx4 v[222:223], v[48:51], off offset:528
	global_store_dwordx4 v[224:225], v[44:47], off
	global_store_dwordx4 v[224:225], v[40:43], off offset:16
	global_store_dwordx4 v[224:225], v[36:39], off offset:512
	global_store_dwordx4 v[224:225], v[32:35], off offset:528
	global_store_dwordx4 v[226:227], v[144:147], off
	global_store_dwordx4 v[226:227], v[148:151], off offset:16
	global_store_dwordx4 v[226:227], v[24:27], off offset:512
	global_store_dwordx4 v[226:227], v[28:31], off offset:528
	global_store_dwordx4 v[190:191], v[12:15], off
	global_store_dwordx4 v[190:191], v[8:11], off offset:16
	global_store_dwordx4 v[190:191], v[0:3], off offset:512
	global_store_dwordx4 v[190:191], v[4:7], off offset:528
	s_waitcnt lgkmcnt(0)
	v_add_f32_e32 v16, v16, v17
	ds_bpermute_b32 v17, v214, v16
	s_and_saveexec_b64 s[12:13], s[0:1]
	s_cbranch_execz .LBB0_1429
	s_waitcnt lgkmcnt(0)
	v_add_f32_e32 v16, v16, v17
	ds_write_b32 v186, v16
